# attention: all fill VALU between the two MFMAs of a fragment step
# speedup vs baseline: 1.0086x; 1.0007x over previous
.Lattn_loop:
	s_waitcnt lgkmcnt(6)
	v_mfma_f32_16x16x32_bf16 v[192:195], v[166:169], v[98:101], 0
	v_add_f32_e32 v130, v66, v67
	v_add_f32_e32 v131, v68, v69
	v_add_f32_e32 v130, v70, v130
	v_mfma_f32_16x16x32_bf16 v[208:211], v[166:169], v[114:117], 0
	ds_read_b128 v[166:169], v185 offset:49152
	s_add_i32 m0, s45, 0x18000
	s_nop 0
	global_load_lds_dwordx4 v152, s[64:65]
	v_mfma_f32_16x16x32_bf16 v[196:199], v[170:173], v[98:101], 0
	v_add_f32_e32 v131, v71, v131
	v_add_f32_e32 v130, v72, v130
	v_add_f32_e32 v131, v73, v131
	v_mfma_f32_16x16x32_bf16 v[212:215], v[170:173], v[114:117], 0
	ds_read_b128 v[170:173], v185 offset:53248
	s_add_i32 m0, s45, 0x1c000
	s_nop 0
	global_load_lds_dwordx4 v150, s[62:63]
	s_waitcnt lgkmcnt(6)
	v_mfma_f32_16x16x32_bf16 v[200:203], v[174:177], v[98:101], 0
	v_add_f32_e32 v130, v74, v130
	v_add_f32_e32 v131, v75, v131
	v_add_f32_e32 v130, v76, v130
	v_mfma_f32_16x16x32_bf16 v[216:219], v[174:177], v[114:117], 0
	ds_read_b128 v[174:177], v185 offset:57344
	s_add_i32 m0, s45, 0x1a000
	s_nop 0
	global_load_lds_dwordx4 v153, s[64:65]
	v_mfma_f32_16x16x32_bf16 v[204:207], v[178:181], v[98:101], 0
	v_add_f32_e32 v131, v77, v131
	v_add_f32_e32 v130, v78, v130
	v_add_f32_e32 v131, v79, v131
	v_mfma_f32_16x16x32_bf16 v[220:223], v[178:181], v[114:117], 0
	ds_read_b128 v[178:181], v185 offset:61440
	s_add_i32 m0, s45, 0x1e000
	s_nop 0
	global_load_lds_dwordx4 v151, s[62:63]
	s_add_u32 s62, s62, 0x4000
	s_addc_u32 s63, s63, 0
	s_add_u32 s64, s64, 0x4000
	s_addc_u32 s65, s65, 0
	s_waitcnt lgkmcnt(6)
	v_mfma_f32_16x16x32_bf16 v[192:195], v[224:227], v[102:105], v[192:195]
	v_add_f32_e32 v130, v80, v130
	v_add_f32_e32 v131, v81, v131
	v_add_f32_e32 v130, v130, v131
	v_mfma_f32_16x16x32_bf16 v[208:211], v[224:227], v[118:121], v[208:211]
	ds_read_b128 v[224:227], v186 offset:49152
	v_mfma_f32_16x16x32_bf16 v[196:199], v[228:231], v[102:105], v[196:199]
	v_add_f32_e32 v165, v165, v130
	v_add_f32_e32 v132, v82, v83
	v_add_f32_e32 v133, v84, v85
	v_mfma_f32_16x16x32_bf16 v[212:215], v[228:231], v[118:121], v[212:215]
	ds_read_b128 v[228:231], v186 offset:53248
	s_waitcnt lgkmcnt(6)
	v_mfma_f32_16x16x32_bf16 v[200:203], v[232:235], v[102:105], v[200:203]
	v_add_f32_e32 v132, v86, v132
	v_add_f32_e32 v133, v87, v133
	v_add_f32_e32 v132, v88, v132
	v_mfma_f32_16x16x32_bf16 v[216:219], v[232:235], v[118:121], v[216:219]
	ds_read_b128 v[232:235], v186 offset:57344
	v_mfma_f32_16x16x32_bf16 v[204:207], v[236:239], v[102:105], v[204:207]
	v_add_f32_e32 v133, v89, v133
	v_add_f32_e32 v132, v90, v132
	v_add_f32_e32 v133, v91, v133
	v_mfma_f32_16x16x32_bf16 v[220:223], v[236:239], v[118:121], v[220:223]
	ds_read_b128 v[236:239], v186 offset:61440
	s_waitcnt lgkmcnt(6)
	v_mfma_f32_16x16x32_bf16 v[192:195], v[166:169], v[106:109], v[192:195]
	v_add_f32_e32 v132, v92, v132
	v_add_f32_e32 v133, v93, v133
	v_add_f32_e32 v132, v94, v132
	v_mfma_f32_16x16x32_bf16 v[208:211], v[166:169], v[122:125], v[208:211]
	ds_read_b64_tr_b16 v[166:167], v240 offset:0
	ds_read_b64_tr_b16 v[168:169], v240 offset:4096
	v_mfma_f32_16x16x32_bf16 v[196:199], v[170:173], v[106:109], v[196:199]
	v_add_f32_e32 v133, v95, v133
	v_add_f32_e32 v132, v96, v132
	v_add_f32_e32 v133, v97, v133
	v_mfma_f32_16x16x32_bf16 v[212:215], v[170:173], v[122:125], v[212:215]
	ds_read_b64_tr_b16 v[170:171], v241 offset:0
	ds_read_b64_tr_b16 v[172:173], v241 offset:4096
	s_waitcnt lgkmcnt(8)
	v_mfma_f32_16x16x32_bf16 v[200:203], v[174:177], v[106:109], v[200:203]
	v_add_f32_e32 v132, v132, v133
	v_add_f32_e32 v163, v163, v132
	v_cvt_pk_bf16_f32 v66, v66, v67
	v_mfma_f32_16x16x32_bf16 v[216:219], v[174:177], v[122:125], v[216:219]
	ds_read_b64_tr_b16 v[174:175], v242 offset:0
	ds_read_b64_tr_b16 v[176:177], v242 offset:4096
	v_mfma_f32_16x16x32_bf16 v[204:207], v[178:181], v[106:109], v[204:207]
	v_cvt_pk_bf16_f32 v67, v68, v69
	v_cvt_pk_bf16_f32 v68, v70, v71
	v_cvt_pk_bf16_f32 v69, v72, v73
	v_mfma_f32_16x16x32_bf16 v[220:223], v[178:181], v[122:125], v[220:223]
	ds_read_b64_tr_b16 v[178:179], v243 offset:0
	ds_read_b64_tr_b16 v[180:181], v243 offset:4096
	s_waitcnt lgkmcnt(10)
	v_mfma_f32_16x16x32_bf16 v[192:195], v[224:227], v[110:113], v[192:195]
	v_cvt_pk_bf16_f32 v74, v74, v75
	v_cvt_pk_bf16_f32 v75, v76, v77
	v_cvt_pk_bf16_f32 v76, v78, v79
	v_mfma_f32_16x16x32_bf16 v[208:211], v[224:227], v[126:129], v[208:211]
	ds_read_b64_tr_b16 v[224:225], v244 offset:0
	ds_read_b64_tr_b16 v[226:227], v244 offset:4096
	v_mfma_f32_16x16x32_bf16 v[196:199], v[228:231], v[110:113], v[196:199]
	v_cvt_pk_bf16_f32 v77, v80, v81
	v_cvt_pk_bf16_f32 v82, v82, v83
	v_cvt_pk_bf16_f32 v83, v84, v85
	v_mfma_f32_16x16x32_bf16 v[212:215], v[228:231], v[126:129], v[212:215]
	s_waitcnt lgkmcnt(10)
	v_mfma_f32_16x16x32_bf16 v[200:203], v[232:235], v[110:113], v[200:203]
	v_cvt_pk_bf16_f32 v84, v86, v87
	v_cvt_pk_bf16_f32 v85, v88, v89
	v_cvt_pk_bf16_f32 v90, v90, v91
	v_mfma_f32_16x16x32_bf16 v[216:219], v[232:235], v[126:129], v[216:219]
	v_mfma_f32_16x16x32_bf16 v[204:207], v[236:239], v[110:113], v[204:207]
	v_cvt_pk_bf16_f32 v91, v92, v93
	v_cvt_pk_bf16_f32 v92, v94, v95
	v_cvt_pk_bf16_f32 v93, v96, v97
	v_mfma_f32_16x16x32_bf16 v[220:223], v[236:239], v[126:129], v[220:223]
	s_waitcnt lgkmcnt(6)
	v_mfma_f32_16x16x32_bf16 v[2:5], v[66:69], v[166:169], v[2:5]
	v_mfma_f32_16x16x32_bf16 v[34:37], v[82:85], v[166:169], v[34:37]
	ds_read_b64_tr_b16 v[228:229], v245 offset:0
	ds_read_b64_tr_b16 v[230:231], v245 offset:4096
	v_mfma_f32_16x16x32_bf16 v[6:9], v[66:69], v[170:173], v[6:9]
	v_mfma_f32_16x16x32_bf16 v[38:41], v[82:85], v[170:173], v[38:41]
	ds_read_b64_tr_b16 v[232:233], v246 offset:0
	ds_read_b64_tr_b16 v[234:235], v246 offset:4096
	s_waitcnt lgkmcnt(6)
	v_mfma_f32_16x16x32_bf16 v[10:13], v[66:69], v[174:177], v[10:13]
	v_exp_f32_e32 v192, v192
	v_exp_f32_e32 v193, v193
	v_exp_f32_e32 v194, v194
	v_mfma_f32_16x16x32_bf16 v[42:45], v[82:85], v[174:177], v[42:45]
	ds_read_b64_tr_b16 v[236:237], v247 offset:0
	ds_read_b64_tr_b16 v[238:239], v247 offset:4096
	v_mfma_f32_16x16x32_bf16 v[14:17], v[66:69], v[178:181], v[14:17]
	v_exp_f32_e32 v195, v195
	v_exp_f32_e32 v208, v208
	v_mfma_f32_16x16x32_bf16 v[46:49], v[82:85], v[178:181], v[46:49]
	ds_read_b64_tr_b16 v[166:167], v240 offset:8192
	ds_read_b64_tr_b16 v[168:169], v240 offset:12288
	s_waitcnt lgkmcnt(6)
	v_mfma_f32_16x16x32_bf16 v[18:21], v[66:69], v[224:227], v[18:21]
	v_exp_f32_e32 v209, v209
	v_exp_f32_e32 v210, v210
	v_mfma_f32_16x16x32_bf16 v[50:53], v[82:85], v[224:227], v[50:53]
	ds_read_b64_tr_b16 v[170:171], v241 offset:8192
	ds_read_b64_tr_b16 v[172:173], v241 offset:12288
	v_mfma_f32_16x16x32_bf16 v[22:25], v[66:69], v[228:231], v[22:25]
	v_exp_f32_e32 v211, v211
	v_exp_f32_e32 v196, v196
	v_exp_f32_e32 v197, v197
	v_mfma_f32_16x16x32_bf16 v[54:57], v[82:85], v[228:231], v[54:57]
	ds_read_b64_tr_b16 v[174:175], v242 offset:8192
	ds_read_b64_tr_b16 v[176:177], v242 offset:12288
	s_waitcnt lgkmcnt(6)
	v_mfma_f32_16x16x32_bf16 v[26:29], v[66:69], v[232:235], v[26:29]
	v_exp_f32_e32 v198, v198
	v_exp_f32_e32 v199, v199
	v_mfma_f32_16x16x32_bf16 v[58:61], v[82:85], v[232:235], v[58:61]
	ds_read_b64_tr_b16 v[178:179], v243 offset:8192
	ds_read_b64_tr_b16 v[180:181], v243 offset:12288
	v_mfma_f32_16x16x32_bf16 v[30:33], v[66:69], v[236:239], v[30:33]
	v_exp_f32_e32 v212, v212
	v_exp_f32_e32 v213, v213
	v_mfma_f32_16x16x32_bf16 v[62:65], v[82:85], v[236:239], v[62:65]
	ds_read_b64_tr_b16 v[224:225], v244 offset:8192
	ds_read_b64_tr_b16 v[226:227], v244 offset:12288
	s_waitcnt lgkmcnt(6)
	v_mfma_f32_16x16x32_bf16 v[2:5], v[74:77], v[166:169], v[2:5]
	v_exp_f32_e32 v214, v214
	v_exp_f32_e32 v215, v215
	v_mfma_f32_16x16x32_bf16 v[34:37], v[90:93], v[166:169], v[34:37]
	ds_read_b64_tr_b16 v[228:229], v245 offset:8192
	ds_read_b64_tr_b16 v[230:231], v245 offset:12288
	ds_read_b128 v[166:169], v187 offset:16384
	v_mfma_f32_16x16x32_bf16 v[6:9], v[74:77], v[170:173], v[6:9]
	v_exp_f32_e32 v200, v200
	v_exp_f32_e32 v201, v201
	v_exp_f32_e32 v202, v202
	v_mfma_f32_16x16x32_bf16 v[38:41], v[90:93], v[170:173], v[38:41]
	ds_read_b64_tr_b16 v[232:233], v246 offset:8192
	ds_read_b64_tr_b16 v[234:235], v246 offset:12288
	ds_read_b128 v[170:173], v187 offset:20480
	s_waitcnt lgkmcnt(8)
	v_mfma_f32_16x16x32_bf16 v[10:13], v[74:77], v[174:177], v[10:13]
	v_exp_f32_e32 v203, v203
	v_exp_f32_e32 v216, v216
	v_mfma_f32_16x16x32_bf16 v[42:45], v[90:93], v[174:177], v[42:45]
	ds_read_b64_tr_b16 v[236:237], v247 offset:8192
	ds_read_b64_tr_b16 v[238:239], v247 offset:12288
	ds_read_b128 v[174:177], v187 offset:24576
	v_mfma_f32_16x16x32_bf16 v[14:17], v[74:77], v[178:181], v[14:17]
	v_exp_f32_e32 v217, v217
	v_exp_f32_e32 v218, v218
	v_mfma_f32_16x16x32_bf16 v[46:49], v[90:93], v[178:181], v[46:49]
	ds_read_b128 v[178:181], v187 offset:28672
	s_waitcnt lgkmcnt(8)
	v_mfma_f32_16x16x32_bf16 v[18:21], v[74:77], v[224:227], v[18:21]
	v_exp_f32_e32 v219, v219
	v_exp_f32_e32 v204, v204
	v_exp_f32_e32 v205, v205
	v_mfma_f32_16x16x32_bf16 v[50:53], v[90:93], v[224:227], v[50:53]
	ds_read_b128 v[224:227], v188 offset:16384
	v_mfma_f32_16x16x32_bf16 v[22:25], v[74:77], v[228:231], v[22:25]
	v_exp_f32_e32 v206, v206
	v_exp_f32_e32 v207, v207
	v_mfma_f32_16x16x32_bf16 v[54:57], v[90:93], v[228:231], v[54:57]
	ds_read_b128 v[228:231], v188 offset:20480
	s_waitcnt lgkmcnt(4)
	v_mfma_f32_16x16x32_bf16 v[26:29], v[74:77], v[232:235], v[26:29]
	v_exp_f32_e32 v220, v220
	v_exp_f32_e32 v221, v221
	v_mfma_f32_16x16x32_bf16 v[58:61], v[90:93], v[232:235], v[58:61]
	ds_read_b128 v[232:235], v188 offset:24576
	v_mfma_f32_16x16x32_bf16 v[30:33], v[74:77], v[236:239], v[30:33]
	v_exp_f32_e32 v222, v222
	v_exp_f32_e32 v223, v223
	v_mfma_f32_16x16x32_bf16 v[62:65], v[90:93], v[236:239], v[62:65]
	ds_read_b128 v[236:239], v188 offset:28672
	s_waitcnt vmcnt(0)
	s_barrier
	v_mfma_f32_16x16x32_bf16 v[66:69], v[166:169], v[98:101], 0
	v_add_f32_e32 v130, v192, v193
	v_add_f32_e32 v131, v194, v195
	v_add_f32_e32 v130, v196, v130
	v_mfma_f32_16x16x32_bf16 v[82:85], v[166:169], v[114:117], 0
	ds_read_b128 v[166:169], v189 offset:16384
	s_add_i32 m0, s45, 0x0
	s_nop 0
	global_load_lds_dwordx4 v152, s[64:65]
	v_mfma_f32_16x16x32_bf16 v[70:73], v[170:173], v[98:101], 0
	v_add_f32_e32 v131, v197, v131
	v_add_f32_e32 v130, v198, v130
	v_add_f32_e32 v131, v199, v131
	v_mfma_f32_16x16x32_bf16 v[86:89], v[170:173], v[114:117], 0
	ds_read_b128 v[170:173], v189 offset:20480
	s_add_i32 m0, s45, 0x4000
	s_nop 0
	global_load_lds_dwordx4 v150, s[62:63]
	s_waitcnt lgkmcnt(6)
	v_mfma_f32_16x16x32_bf16 v[74:77], v[174:177], v[98:101], 0
	v_add_f32_e32 v130, v200, v130
	v_add_f32_e32 v131, v201, v131
	v_add_f32_e32 v130, v202, v130
	v_mfma_f32_16x16x32_bf16 v[90:93], v[174:177], v[114:117], 0
	ds_read_b128 v[174:177], v189 offset:24576
	s_add_i32 m0, s45, 0x2000
	s_nop 0
	global_load_lds_dwordx4 v153, s[64:65]
	v_mfma_f32_16x16x32_bf16 v[78:81], v[178:181], v[98:101], 0
	v_add_f32_e32 v131, v203, v131
	v_add_f32_e32 v130, v204, v130
	v_add_f32_e32 v131, v205, v131
	v_mfma_f32_16x16x32_bf16 v[94:97], v[178:181], v[114:117], 0
	ds_read_b128 v[178:181], v189 offset:28672
	s_add_i32 m0, s45, 0x6000
	s_nop 0
	global_load_lds_dwordx4 v151, s[62:63]
	s_add_u32 s62, s62, 0x4000
	s_addc_u32 s63, s63, 0
	s_add_u32 s64, s64, 0x4000
	s_addc_u32 s65, s65, 0
	s_waitcnt lgkmcnt(6)
	v_mfma_f32_16x16x32_bf16 v[66:69], v[224:227], v[102:105], v[66:69]
	v_add_f32_e32 v130, v206, v130
	v_add_f32_e32 v131, v207, v131
	v_add_f32_e32 v130, v130, v131
	v_mfma_f32_16x16x32_bf16 v[82:85], v[224:227], v[118:121], v[82:85]
	ds_read_b128 v[224:227], v190 offset:16384
	v_mfma_f32_16x16x32_bf16 v[70:73], v[228:231], v[102:105], v[70:73]
	v_add_f32_e32 v165, v165, v130
	v_add_f32_e32 v132, v208, v209
	v_add_f32_e32 v133, v210, v211
	v_mfma_f32_16x16x32_bf16 v[86:89], v[228:231], v[118:121], v[86:89]
	ds_read_b128 v[228:231], v190 offset:20480
	s_waitcnt lgkmcnt(6)
	v_mfma_f32_16x16x32_bf16 v[74:77], v[232:235], v[102:105], v[74:77]
	v_add_f32_e32 v132, v212, v132
	v_add_f32_e32 v133, v213, v133
	v_add_f32_e32 v132, v214, v132
	v_mfma_f32_16x16x32_bf16 v[90:93], v[232:235], v[118:121], v[90:93]
	ds_read_b128 v[232:235], v190 offset:24576
	v_mfma_f32_16x16x32_bf16 v[78:81], v[236:239], v[102:105], v[78:81]
	v_add_f32_e32 v133, v215, v133
	v_add_f32_e32 v132, v216, v132
	v_add_f32_e32 v133, v217, v133
	v_mfma_f32_16x16x32_bf16 v[94:97], v[236:239], v[118:121], v[94:97]
	ds_read_b128 v[236:239], v190 offset:28672
	s_waitcnt lgkmcnt(6)
	v_mfma_f32_16x16x32_bf16 v[66:69], v[166:169], v[106:109], v[66:69]
	v_add_f32_e32 v132, v218, v132
	v_add_f32_e32 v133, v219, v133
	v_add_f32_e32 v132, v220, v132
	v_mfma_f32_16x16x32_bf16 v[82:85], v[166:169], v[122:125], v[82:85]
	ds_read_b64_tr_b16 v[166:167], v240 offset:32768
	ds_read_b64_tr_b16 v[168:169], v240 offset:36864
	v_mfma_f32_16x16x32_bf16 v[70:73], v[170:173], v[106:109], v[70:73]
	v_add_f32_e32 v133, v221, v133
	v_add_f32_e32 v132, v222, v132
	v_add_f32_e32 v133, v223, v133
	v_mfma_f32_16x16x32_bf16 v[86:89], v[170:173], v[122:125], v[86:89]
	ds_read_b64_tr_b16 v[170:171], v241 offset:32768
	ds_read_b64_tr_b16 v[172:173], v241 offset:36864
	s_waitcnt lgkmcnt(8)
	v_mfma_f32_16x16x32_bf16 v[74:77], v[174:177], v[106:109], v[74:77]
	v_add_f32_e32 v132, v132, v133
	v_add_f32_e32 v163, v163, v132
	v_cvt_pk_bf16_f32 v192, v192, v193
	v_mfma_f32_16x16x32_bf16 v[90:93], v[174:177], v[122:125], v[90:93]
	ds_read_b64_tr_b16 v[174:175], v242 offset:32768
	ds_read_b64_tr_b16 v[176:177], v242 offset:36864
	v_mfma_f32_16x16x32_bf16 v[78:81], v[178:181], v[106:109], v[78:81]
	v_cvt_pk_bf16_f32 v193, v194, v195
	v_cvt_pk_bf16_f32 v194, v196, v197
	v_cvt_pk_bf16_f32 v195, v198, v199
	v_mfma_f32_16x16x32_bf16 v[94:97], v[178:181], v[122:125], v[94:97]
	ds_read_b64_tr_b16 v[178:179], v243 offset:32768
	ds_read_b64_tr_b16 v[180:181], v243 offset:36864
	s_waitcnt lgkmcnt(10)
	v_mfma_f32_16x16x32_bf16 v[66:69], v[224:227], v[110:113], v[66:69]
	v_cvt_pk_bf16_f32 v200, v200, v201
	v_cvt_pk_bf16_f32 v201, v202, v203
	v_cvt_pk_bf16_f32 v202, v204, v205
	v_mfma_f32_16x16x32_bf16 v[82:85], v[224:227], v[126:129], v[82:85]
	ds_read_b64_tr_b16 v[224:225], v244 offset:32768
	ds_read_b64_tr_b16 v[226:227], v244 offset:36864
	v_mfma_f32_16x16x32_bf16 v[70:73], v[228:231], v[110:113], v[70:73]
	v_cvt_pk_bf16_f32 v203, v206, v207
	v_cvt_pk_bf16_f32 v208, v208, v209
	v_cvt_pk_bf16_f32 v209, v210, v211
	v_mfma_f32_16x16x32_bf16 v[86:89], v[228:231], v[126:129], v[86:89]
	s_waitcnt lgkmcnt(10)
	v_mfma_f32_16x16x32_bf16 v[74:77], v[232:235], v[110:113], v[74:77]
	v_cvt_pk_bf16_f32 v210, v212, v213
	v_cvt_pk_bf16_f32 v211, v214, v215
	v_cvt_pk_bf16_f32 v216, v216, v217
	v_mfma_f32_16x16x32_bf16 v[90:93], v[232:235], v[126:129], v[90:93]
	v_mfma_f32_16x16x32_bf16 v[78:81], v[236:239], v[110:113], v[78:81]
	v_cvt_pk_bf16_f32 v217, v218, v219
	v_cvt_pk_bf16_f32 v218, v220, v221
	v_cvt_pk_bf16_f32 v219, v222, v223
	v_mfma_f32_16x16x32_bf16 v[94:97], v[236:239], v[126:129], v[94:97]
	s_waitcnt lgkmcnt(6)
	v_mfma_f32_16x16x32_bf16 v[2:5], v[192:195], v[166:169], v[2:5]
	v_mfma_f32_16x16x32_bf16 v[34:37], v[208:211], v[166:169], v[34:37]
	ds_read_b64_tr_b16 v[228:229], v245 offset:32768
	ds_read_b64_tr_b16 v[230:231], v245 offset:36864
	v_mfma_f32_16x16x32_bf16 v[6:9], v[192:195], v[170:173], v[6:9]
	v_mfma_f32_16x16x32_bf16 v[38:41], v[208:211], v[170:173], v[38:41]
	ds_read_b64_tr_b16 v[232:233], v246 offset:32768
	ds_read_b64_tr_b16 v[234:235], v246 offset:36864
	s_waitcnt lgkmcnt(6)
	v_mfma_f32_16x16x32_bf16 v[10:13], v[192:195], v[174:177], v[10:13]
	v_exp_f32_e32 v66, v66
	v_exp_f32_e32 v67, v67
	v_exp_f32_e32 v68, v68
	v_mfma_f32_16x16x32_bf16 v[42:45], v[208:211], v[174:177], v[42:45]
	ds_read_b64_tr_b16 v[236:237], v247 offset:32768
	ds_read_b64_tr_b16 v[238:239], v247 offset:36864
	v_mfma_f32_16x16x32_bf16 v[14:17], v[192:195], v[178:181], v[14:17]
	v_exp_f32_e32 v69, v69
	v_exp_f32_e32 v82, v82
	v_mfma_f32_16x16x32_bf16 v[46:49], v[208:211], v[178:181], v[46:49]
	ds_read_b64_tr_b16 v[166:167], v240 offset:40960
	ds_read_b64_tr_b16 v[168:169], v240 offset:45056
	s_waitcnt lgkmcnt(6)
	v_mfma_f32_16x16x32_bf16 v[18:21], v[192:195], v[224:227], v[18:21]
	v_exp_f32_e32 v83, v83
	v_exp_f32_e32 v84, v84
	v_mfma_f32_16x16x32_bf16 v[50:53], v[208:211], v[224:227], v[50:53]
	ds_read_b64_tr_b16 v[170:171], v241 offset:40960
	ds_read_b64_tr_b16 v[172:173], v241 offset:45056
	v_mfma_f32_16x16x32_bf16 v[22:25], v[192:195], v[228:231], v[22:25]
	v_exp_f32_e32 v85, v85
	v_exp_f32_e32 v70, v70
	v_exp_f32_e32 v71, v71
	v_mfma_f32_16x16x32_bf16 v[54:57], v[208:211], v[228:231], v[54:57]
	ds_read_b64_tr_b16 v[174:175], v242 offset:40960
	ds_read_b64_tr_b16 v[176:177], v242 offset:45056
	s_waitcnt lgkmcnt(6)
	v_mfma_f32_16x16x32_bf16 v[26:29], v[192:195], v[232:235], v[26:29]
	v_exp_f32_e32 v72, v72
	v_exp_f32_e32 v73, v73
	v_mfma_f32_16x16x32_bf16 v[58:61], v[208:211], v[232:235], v[58:61]
	ds_read_b64_tr_b16 v[178:179], v243 offset:40960
	ds_read_b64_tr_b16 v[180:181], v243 offset:45056
	v_mfma_f32_16x16x32_bf16 v[30:33], v[192:195], v[236:239], v[30:33]
	v_exp_f32_e32 v86, v86
	v_exp_f32_e32 v87, v87
	v_mfma_f32_16x16x32_bf16 v[62:65], v[208:211], v[236:239], v[62:65]
	ds_read_b64_tr_b16 v[224:225], v244 offset:40960
	ds_read_b64_tr_b16 v[226:227], v244 offset:45056
	s_waitcnt lgkmcnt(6)
	v_mfma_f32_16x16x32_bf16 v[2:5], v[200:203], v[166:169], v[2:5]
	v_exp_f32_e32 v88, v88
	v_exp_f32_e32 v89, v89
	v_mfma_f32_16x16x32_bf16 v[34:37], v[216:219], v[166:169], v[34:37]
	ds_read_b64_tr_b16 v[228:229], v245 offset:40960
	ds_read_b64_tr_b16 v[230:231], v245 offset:45056
	ds_read_b128 v[166:169], v187 offset:49152
	v_mfma_f32_16x16x32_bf16 v[6:9], v[200:203], v[170:173], v[6:9]
	v_exp_f32_e32 v74, v74
	v_exp_f32_e32 v75, v75
	v_exp_f32_e32 v76, v76
	v_mfma_f32_16x16x32_bf16 v[38:41], v[216:219], v[170:173], v[38:41]
	ds_read_b64_tr_b16 v[232:233], v246 offset:40960
	ds_read_b64_tr_b16 v[234:235], v246 offset:45056
	ds_read_b128 v[170:173], v187 offset:53248
	s_waitcnt lgkmcnt(8)
	v_mfma_f32_16x16x32_bf16 v[10:13], v[200:203], v[174:177], v[10:13]
	v_exp_f32_e32 v77, v77
	v_exp_f32_e32 v90, v90
	v_mfma_f32_16x16x32_bf16 v[42:45], v[216:219], v[174:177], v[42:45]
	ds_read_b64_tr_b16 v[236:237], v247 offset:40960
	ds_read_b64_tr_b16 v[238:239], v247 offset:45056
	ds_read_b128 v[174:177], v187 offset:57344
	v_mfma_f32_16x16x32_bf16 v[14:17], v[200:203], v[178:181], v[14:17]
	v_exp_f32_e32 v91, v91
	v_exp_f32_e32 v92, v92
	v_mfma_f32_16x16x32_bf16 v[46:49], v[216:219], v[178:181], v[46:49]
	ds_read_b128 v[178:181], v187 offset:61440
	s_waitcnt lgkmcnt(8)
	v_mfma_f32_16x16x32_bf16 v[18:21], v[200:203], v[224:227], v[18:21]
	v_exp_f32_e32 v93, v93
	v_exp_f32_e32 v78, v78
	v_exp_f32_e32 v79, v79
	v_mfma_f32_16x16x32_bf16 v[50:53], v[216:219], v[224:227], v[50:53]
	ds_read_b128 v[224:227], v188 offset:49152
	v_mfma_f32_16x16x32_bf16 v[22:25], v[200:203], v[228:231], v[22:25]
	v_exp_f32_e32 v80, v80
	v_exp_f32_e32 v81, v81
	v_mfma_f32_16x16x32_bf16 v[54:57], v[216:219], v[228:231], v[54:57]
	ds_read_b128 v[228:231], v188 offset:53248
	s_waitcnt lgkmcnt(4)
	v_mfma_f32_16x16x32_bf16 v[26:29], v[200:203], v[232:235], v[26:29]
	v_exp_f32_e32 v94, v94
	v_exp_f32_e32 v95, v95
	v_mfma_f32_16x16x32_bf16 v[58:61], v[216:219], v[232:235], v[58:61]
	ds_read_b128 v[232:235], v188 offset:57344
	v_mfma_f32_16x16x32_bf16 v[30:33], v[200:203], v[236:239], v[30:33]
	v_exp_f32_e32 v96, v96
	v_exp_f32_e32 v97, v97
	v_mfma_f32_16x16x32_bf16 v[62:65], v[216:219], v[236:239], v[62:65]
	ds_read_b128 v[236:239], v188 offset:61440
	s_waitcnt vmcnt(0)
	s_barrier
	v_mfma_f32_16x16x32_bf16 v[192:195], v[166:169], v[98:101], 0
	v_add_f32_e32 v130, v66, v67
	v_add_f32_e32 v131, v68, v69
	v_add_f32_e32 v130, v70, v130
	v_mfma_f32_16x16x32_bf16 v[208:211], v[166:169], v[114:117], 0
	ds_read_b128 v[166:169], v189 offset:49152
	s_add_i32 m0, s45, 0x8000
	s_nop 0
	global_load_lds_dwordx4 v152, s[64:65]
	v_mfma_f32_16x16x32_bf16 v[196:199], v[170:173], v[98:101], 0
	v_add_f32_e32 v131, v71, v131
	v_add_f32_e32 v130, v72, v130
	v_add_f32_e32 v131, v73, v131
	v_mfma_f32_16x16x32_bf16 v[212:215], v[170:173], v[114:117], 0
	ds_read_b128 v[170:173], v189 offset:53248
	s_add_i32 m0, s45, 0xc000
	s_nop 0
	global_load_lds_dwordx4 v150, s[62:63]
	s_waitcnt lgkmcnt(6)
	v_mfma_f32_16x16x32_bf16 v[200:203], v[174:177], v[98:101], 0
	v_add_f32_e32 v130, v74, v130
	v_add_f32_e32 v131, v75, v131
	v_add_f32_e32 v130, v76, v130
	v_mfma_f32_16x16x32_bf16 v[216:219], v[174:177], v[114:117], 0
	ds_read_b128 v[174:177], v189 offset:57344
	s_add_i32 m0, s45, 0xa000
	s_nop 0
	global_load_lds_dwordx4 v153, s[64:65]
	v_mfma_f32_16x16x32_bf16 v[204:207], v[178:181], v[98:101], 0
	v_add_f32_e32 v131, v77, v131
	v_add_f32_e32 v130, v78, v130
	v_add_f32_e32 v131, v79, v131
	v_mfma_f32_16x16x32_bf16 v[220:223], v[178:181], v[114:117], 0
	ds_read_b128 v[178:181], v189 offset:61440
	s_add_i32 m0, s45, 0xe000
	s_nop 0
	global_load_lds_dwordx4 v151, s[62:63]
	s_add_u32 s62, s62, 0x4000
	s_addc_u32 s63, s63, 0
	s_add_u32 s64, s64, 0x4000
	s_addc_u32 s65, s65, 0
	s_waitcnt lgkmcnt(6)
	v_mfma_f32_16x16x32_bf16 v[192:195], v[224:227], v[102:105], v[192:195]
	v_add_f32_e32 v130, v80, v130
	v_add_f32_e32 v131, v81, v131
	v_add_f32_e32 v130, v130, v131
	v_mfma_f32_16x16x32_bf16 v[208:211], v[224:227], v[118:121], v[208:211]
	ds_read_b128 v[224:227], v190 offset:49152
	v_mfma_f32_16x16x32_bf16 v[196:199], v[228:231], v[102:105], v[196:199]
	v_add_f32_e32 v165, v165, v130
	v_add_f32_e32 v132, v82, v83
	v_add_f32_e32 v133, v84, v85
	v_mfma_f32_16x16x32_bf16 v[212:215], v[228:231], v[118:121], v[212:215]
	ds_read_b128 v[228:231], v190 offset:53248
	s_waitcnt lgkmcnt(6)
	v_mfma_f32_16x16x32_bf16 v[200:203], v[232:235], v[102:105], v[200:203]
	v_add_f32_e32 v132, v86, v132
	v_add_f32_e32 v133, v87, v133
	v_add_f32_e32 v132, v88, v132
	v_mfma_f32_16x16x32_bf16 v[216:219], v[232:235], v[118:121], v[216:219]
	ds_read_b128 v[232:235], v190 offset:57344
	v_mfma_f32_16x16x32_bf16 v[204:207], v[236:239], v[102:105], v[204:207]
	v_add_f32_e32 v133, v89, v133
	v_add_f32_e32 v132, v90, v132
	v_add_f32_e32 v133, v91, v133
	v_mfma_f32_16x16x32_bf16 v[220:223], v[236:239], v[118:121], v[220:223]
	ds_read_b128 v[236:239], v190 offset:61440
	s_waitcnt lgkmcnt(6)
	v_mfma_f32_16x16x32_bf16 v[192:195], v[166:169], v[106:109], v[192:195]
	v_add_f32_e32 v132, v92, v132
	v_add_f32_e32 v133, v93, v133
	v_add_f32_e32 v132, v94, v132
	v_mfma_f32_16x16x32_bf16 v[208:211], v[166:169], v[122:125], v[208:211]
	ds_read_b64_tr_b16 v[166:167], v142 offset:0
	ds_read_b64_tr_b16 v[168:169], v142 offset:4096
	v_mfma_f32_16x16x32_bf16 v[196:199], v[170:173], v[106:109], v[196:199]
	v_add_f32_e32 v133, v95, v133
	v_add_f32_e32 v132, v96, v132
	v_add_f32_e32 v133, v97, v133
	v_mfma_f32_16x16x32_bf16 v[212:215], v[170:173], v[122:125], v[212:215]
	ds_read_b64_tr_b16 v[170:171], v143 offset:0
	ds_read_b64_tr_b16 v[172:173], v143 offset:4096
	s_waitcnt lgkmcnt(8)
	v_mfma_f32_16x16x32_bf16 v[200:203], v[174:177], v[106:109], v[200:203]
	v_add_f32_e32 v132, v132, v133
	v_add_f32_e32 v163, v163, v132
	v_cvt_pk_bf16_f32 v66, v66, v67
	v_mfma_f32_16x16x32_bf16 v[216:219], v[174:177], v[122:125], v[216:219]
	ds_read_b64_tr_b16 v[174:175], v144 offset:0
	ds_read_b64_tr_b16 v[176:177], v144 offset:4096
	v_mfma_f32_16x16x32_bf16 v[204:207], v[178:181], v[106:109], v[204:207]
	v_cvt_pk_bf16_f32 v67, v68, v69
	v_cvt_pk_bf16_f32 v68, v70, v71
	v_cvt_pk_bf16_f32 v69, v72, v73
	v_mfma_f32_16x16x32_bf16 v[220:223], v[178:181], v[122:125], v[220:223]
	ds_read_b64_tr_b16 v[178:179], v145 offset:0
	ds_read_b64_tr_b16 v[180:181], v145 offset:4096
	s_waitcnt lgkmcnt(10)
	v_mfma_f32_16x16x32_bf16 v[192:195], v[224:227], v[110:113], v[192:195]
	v_cvt_pk_bf16_f32 v74, v74, v75
	v_cvt_pk_bf16_f32 v75, v76, v77
	v_cvt_pk_bf16_f32 v76, v78, v79
	v_mfma_f32_16x16x32_bf16 v[208:211], v[224:227], v[126:129], v[208:211]
	ds_read_b64_tr_b16 v[224:225], v146 offset:0
	ds_read_b64_tr_b16 v[226:227], v146 offset:4096
	v_mfma_f32_16x16x32_bf16 v[196:199], v[228:231], v[110:113], v[196:199]
	v_cvt_pk_bf16_f32 v77, v80, v81
	v_cvt_pk_bf16_f32 v82, v82, v83
	v_cvt_pk_bf16_f32 v83, v84, v85
	v_mfma_f32_16x16x32_bf16 v[212:215], v[228:231], v[126:129], v[212:215]
	s_waitcnt lgkmcnt(10)
	v_mfma_f32_16x16x32_bf16 v[200:203], v[232:235], v[110:113], v[200:203]
	v_cvt_pk_bf16_f32 v84, v86, v87
	v_cvt_pk_bf16_f32 v85, v88, v89
	v_cvt_pk_bf16_f32 v90, v90, v91
	v_mfma_f32_16x16x32_bf16 v[216:219], v[232:235], v[126:129], v[216:219]
	v_mfma_f32_16x16x32_bf16 v[204:207], v[236:239], v[110:113], v[204:207]
	v_cvt_pk_bf16_f32 v91, v92, v93
	v_cvt_pk_bf16_f32 v92, v94, v95
	v_cvt_pk_bf16_f32 v93, v96, v97
	v_mfma_f32_16x16x32_bf16 v[220:223], v[236:239], v[126:129], v[220:223]
	s_waitcnt lgkmcnt(6)
	v_mfma_f32_16x16x32_bf16 v[2:5], v[66:69], v[166:169], v[2:5]
	v_mfma_f32_16x16x32_bf16 v[34:37], v[82:85], v[166:169], v[34:37]
	ds_read_b64_tr_b16 v[228:229], v147 offset:0
	ds_read_b64_tr_b16 v[230:231], v147 offset:4096
	v_mfma_f32_16x16x32_bf16 v[6:9], v[66:69], v[170:173], v[6:9]
	v_mfma_f32_16x16x32_bf16 v[38:41], v[82:85], v[170:173], v[38:41]
	ds_read_b64_tr_b16 v[232:233], v148 offset:0
	ds_read_b64_tr_b16 v[234:235], v148 offset:4096
	s_waitcnt lgkmcnt(6)
	v_mfma_f32_16x16x32_bf16 v[10:13], v[66:69], v[174:177], v[10:13]
	v_exp_f32_e32 v192, v192
	v_exp_f32_e32 v193, v193
	v_exp_f32_e32 v194, v194
	v_mfma_f32_16x16x32_bf16 v[42:45], v[82:85], v[174:177], v[42:45]
	ds_read_b64_tr_b16 v[236:237], v149 offset:0
	ds_read_b64_tr_b16 v[238:239], v149 offset:4096
	v_mfma_f32_16x16x32_bf16 v[14:17], v[66:69], v[178:181], v[14:17]
	v_exp_f32_e32 v195, v195
	v_exp_f32_e32 v208, v208
	v_mfma_f32_16x16x32_bf16 v[46:49], v[82:85], v[178:181], v[46:49]
	ds_read_b64_tr_b16 v[166:167], v142 offset:8192
	ds_read_b64_tr_b16 v[168:169], v142 offset:12288
	s_waitcnt lgkmcnt(6)
	v_mfma_f32_16x16x32_bf16 v[18:21], v[66:69], v[224:227], v[18:21]
	v_exp_f32_e32 v209, v209
	v_exp_f32_e32 v210, v210
	v_mfma_f32_16x16x32_bf16 v[50:53], v[82:85], v[224:227], v[50:53]
	ds_read_b64_tr_b16 v[170:171], v143 offset:8192
	ds_read_b64_tr_b16 v[172:173], v143 offset:12288
	v_mfma_f32_16x16x32_bf16 v[22:25], v[66:69], v[228:231], v[22:25]
	v_exp_f32_e32 v211, v211
	v_exp_f32_e32 v196, v196
	v_exp_f32_e32 v197, v197
	v_mfma_f32_16x16x32_bf16 v[54:57], v[82:85], v[228:231], v[54:57]
	ds_read_b64_tr_b16 v[174:175], v144 offset:8192
	ds_read_b64_tr_b16 v[176:177], v144 offset:12288
	s_waitcnt lgkmcnt(6)
	v_mfma_f32_16x16x32_bf16 v[26:29], v[66:69], v[232:235], v[26:29]
	v_exp_f32_e32 v198, v198
	v_exp_f32_e32 v199, v199
	v_mfma_f32_16x16x32_bf16 v[58:61], v[82:85], v[232:235], v[58:61]
	ds_read_b64_tr_b16 v[178:179], v145 offset:8192
	ds_read_b64_tr_b16 v[180:181], v145 offset:12288
	v_mfma_f32_16x16x32_bf16 v[30:33], v[66:69], v[236:239], v[30:33]
	v_exp_f32_e32 v212, v212
	v_exp_f32_e32 v213, v213
	v_mfma_f32_16x16x32_bf16 v[62:65], v[82:85], v[236:239], v[62:65]
	ds_read_b64_tr_b16 v[224:225], v146 offset:8192
	ds_read_b64_tr_b16 v[226:227], v146 offset:12288
	s_waitcnt lgkmcnt(6)
	v_mfma_f32_16x16x32_bf16 v[2:5], v[74:77], v[166:169], v[2:5]
	v_exp_f32_e32 v214, v214
	v_exp_f32_e32 v215, v215
	v_mfma_f32_16x16x32_bf16 v[34:37], v[90:93], v[166:169], v[34:37]
	ds_read_b64_tr_b16 v[228:229], v147 offset:8192
	ds_read_b64_tr_b16 v[230:231], v147 offset:12288
	ds_read_b128 v[166:169], v183 offset:16384
	v_mfma_f32_16x16x32_bf16 v[6:9], v[74:77], v[170:173], v[6:9]
	v_exp_f32_e32 v200, v200
	v_exp_f32_e32 v201, v201
	v_exp_f32_e32 v202, v202
	v_mfma_f32_16x16x32_bf16 v[38:41], v[90:93], v[170:173], v[38:41]
	ds_read_b64_tr_b16 v[232:233], v148 offset:8192
	ds_read_b64_tr_b16 v[234:235], v148 offset:12288
	ds_read_b128 v[170:173], v183 offset:20480
	s_waitcnt lgkmcnt(8)
	v_mfma_f32_16x16x32_bf16 v[10:13], v[74:77], v[174:177], v[10:13]
	v_exp_f32_e32 v203, v203
	v_exp_f32_e32 v216, v216
	v_mfma_f32_16x16x32_bf16 v[42:45], v[90:93], v[174:177], v[42:45]
	ds_read_b64_tr_b16 v[236:237], v149 offset:8192
	ds_read_b64_tr_b16 v[238:239], v149 offset:12288
	ds_read_b128 v[174:177], v183 offset:24576
	v_mfma_f32_16x16x32_bf16 v[14:17], v[74:77], v[178:181], v[14:17]
	v_exp_f32_e32 v217, v217
	v_exp_f32_e32 v218, v218
	v_mfma_f32_16x16x32_bf16 v[46:49], v[90:93], v[178:181], v[46:49]
	ds_read_b128 v[178:181], v183 offset:28672
	s_waitcnt lgkmcnt(8)
	v_mfma_f32_16x16x32_bf16 v[18:21], v[74:77], v[224:227], v[18:21]
	v_exp_f32_e32 v219, v219
	v_exp_f32_e32 v204, v204
	v_exp_f32_e32 v205, v205
	v_mfma_f32_16x16x32_bf16 v[50:53], v[90:93], v[224:227], v[50:53]
	ds_read_b128 v[224:227], v184 offset:16384
	v_mfma_f32_16x16x32_bf16 v[22:25], v[74:77], v[228:231], v[22:25]
	v_exp_f32_e32 v206, v206
	v_exp_f32_e32 v207, v207
	v_mfma_f32_16x16x32_bf16 v[54:57], v[90:93], v[228:231], v[54:57]
	ds_read_b128 v[228:231], v184 offset:20480
	s_waitcnt lgkmcnt(4)
	v_mfma_f32_16x16x32_bf16 v[26:29], v[74:77], v[232:235], v[26:29]
	v_exp_f32_e32 v220, v220
	v_exp_f32_e32 v221, v221
	v_mfma_f32_16x16x32_bf16 v[58:61], v[90:93], v[232:235], v[58:61]
	ds_read_b128 v[232:235], v184 offset:24576
	v_mfma_f32_16x16x32_bf16 v[30:33], v[74:77], v[236:239], v[30:33]
	v_exp_f32_e32 v222, v222
	v_exp_f32_e32 v223, v223
	v_mfma_f32_16x16x32_bf16 v[62:65], v[90:93], v[236:239], v[62:65]
	ds_read_b128 v[236:239], v184 offset:28672
	s_waitcnt vmcnt(0)
	s_barrier
	v_mfma_f32_16x16x32_bf16 v[66:69], v[166:169], v[98:101], 0
	v_add_f32_e32 v130, v192, v193
	v_add_f32_e32 v131, v194, v195
	v_add_f32_e32 v130, v196, v130
	v_mfma_f32_16x16x32_bf16 v[82:85], v[166:169], v[114:117], 0
	ds_read_b128 v[166:169], v185 offset:16384
	s_add_i32 m0, s45, 0x10000
	s_nop 0
	global_load_lds_dwordx4 v152, s[64:65]
	v_mfma_f32_16x16x32_bf16 v[70:73], v[170:173], v[98:101], 0
	v_add_f32_e32 v131, v197, v131
	v_add_f32_e32 v130, v198, v130
	v_add_f32_e32 v131, v199, v131
	v_mfma_f32_16x16x32_bf16 v[86:89], v[170:173], v[114:117], 0
	ds_read_b128 v[170:173], v185 offset:20480
	s_add_i32 m0, s45, 0x14000
	s_nop 0
	global_load_lds_dwordx4 v150, s[62:63]
	s_waitcnt lgkmcnt(6)
	v_mfma_f32_16x16x32_bf16 v[74:77], v[174:177], v[98:101], 0
	v_add_f32_e32 v130, v200, v130
	v_add_f32_e32 v131, v201, v131
	v_add_f32_e32 v130, v202, v130
	v_mfma_f32_16x16x32_bf16 v[90:93], v[174:177], v[114:117], 0
	ds_read_b128 v[174:177], v185 offset:24576
	s_add_i32 m0, s45, 0x12000
	s_nop 0
	global_load_lds_dwordx4 v153, s[64:65]
	v_mfma_f32_16x16x32_bf16 v[78:81], v[178:181], v[98:101], 0
	v_add_f32_e32 v131, v203, v131
	v_add_f32_e32 v130, v204, v130
	v_add_f32_e32 v131, v205, v131
	v_mfma_f32_16x16x32_bf16 v[94:97], v[178:181], v[114:117], 0
	ds_read_b128 v[178:181], v185 offset:28672
	s_add_i32 m0, s45, 0x16000
	s_nop 0
	global_load_lds_dwordx4 v151, s[62:63]
	s_add_u32 s62, s62, 0x4000
	s_addc_u32 s63, s63, 0
	s_add_u32 s64, s64, 0x4000
	s_addc_u32 s65, s65, 0
	s_waitcnt lgkmcnt(6)
	v_mfma_f32_16x16x32_bf16 v[66:69], v[224:227], v[102:105], v[66:69]
	v_add_f32_e32 v130, v206, v130
	v_add_f32_e32 v131, v207, v131
	v_add_f32_e32 v130, v130, v131
	v_mfma_f32_16x16x32_bf16 v[82:85], v[224:227], v[118:121], v[82:85]
	ds_read_b128 v[224:227], v186 offset:16384
	v_mfma_f32_16x16x32_bf16 v[70:73], v[228:231], v[102:105], v[70:73]
	v_add_f32_e32 v165, v165, v130
	v_add_f32_e32 v132, v208, v209
	v_add_f32_e32 v133, v210, v211
	v_mfma_f32_16x16x32_bf16 v[86:89], v[228:231], v[118:121], v[86:89]
	ds_read_b128 v[228:231], v186 offset:20480
	s_waitcnt lgkmcnt(6)
	v_mfma_f32_16x16x32_bf16 v[74:77], v[232:235], v[102:105], v[74:77]
	v_add_f32_e32 v132, v212, v132
	v_add_f32_e32 v133, v213, v133
	v_add_f32_e32 v132, v214, v132
	v_mfma_f32_16x16x32_bf16 v[90:93], v[232:235], v[118:121], v[90:93]
	ds_read_b128 v[232:235], v186 offset:24576
	v_mfma_f32_16x16x32_bf16 v[78:81], v[236:239], v[102:105], v[78:81]
	v_add_f32_e32 v133, v215, v133
	v_add_f32_e32 v132, v216, v132
	v_add_f32_e32 v133, v217, v133
	v_mfma_f32_16x16x32_bf16 v[94:97], v[236:239], v[118:121], v[94:97]
	ds_read_b128 v[236:239], v186 offset:28672
	s_waitcnt lgkmcnt(6)
	v_mfma_f32_16x16x32_bf16 v[66:69], v[166:169], v[106:109], v[66:69]
	v_add_f32_e32 v132, v218, v132
	v_add_f32_e32 v133, v219, v133
	v_add_f32_e32 v132, v220, v132
	v_mfma_f32_16x16x32_bf16 v[82:85], v[166:169], v[122:125], v[82:85]
	ds_read_b64_tr_b16 v[166:167], v142 offset:32768
	ds_read_b64_tr_b16 v[168:169], v142 offset:36864
	v_mfma_f32_16x16x32_bf16 v[70:73], v[170:173], v[106:109], v[70:73]
	v_add_f32_e32 v133, v221, v133
	v_add_f32_e32 v132, v222, v132
	v_add_f32_e32 v133, v223, v133
	v_mfma_f32_16x16x32_bf16 v[86:89], v[170:173], v[122:125], v[86:89]
	ds_read_b64_tr_b16 v[170:171], v143 offset:32768
	ds_read_b64_tr_b16 v[172:173], v143 offset:36864
	s_waitcnt lgkmcnt(8)
	v_mfma_f32_16x16x32_bf16 v[74:77], v[174:177], v[106:109], v[74:77]
	v_add_f32_e32 v132, v132, v133
	v_add_f32_e32 v163, v163, v132
	v_cvt_pk_bf16_f32 v192, v192, v193
	v_mfma_f32_16x16x32_bf16 v[90:93], v[174:177], v[122:125], v[90:93]
	ds_read_b64_tr_b16 v[174:175], v144 offset:32768
	ds_read_b64_tr_b16 v[176:177], v144 offset:36864
	v_mfma_f32_16x16x32_bf16 v[78:81], v[178:181], v[106:109], v[78:81]
	v_cvt_pk_bf16_f32 v193, v194, v195
	v_cvt_pk_bf16_f32 v194, v196, v197
	v_cvt_pk_bf16_f32 v195, v198, v199
	v_mfma_f32_16x16x32_bf16 v[94:97], v[178:181], v[122:125], v[94:97]
	ds_read_b64_tr_b16 v[178:179], v145 offset:32768
	ds_read_b64_tr_b16 v[180:181], v145 offset:36864
	s_waitcnt lgkmcnt(10)
	v_mfma_f32_16x16x32_bf16 v[66:69], v[224:227], v[110:113], v[66:69]
	v_cvt_pk_bf16_f32 v200, v200, v201
	v_cvt_pk_bf16_f32 v201, v202, v203
	v_cvt_pk_bf16_f32 v202, v204, v205
	v_mfma_f32_16x16x32_bf16 v[82:85], v[224:227], v[126:129], v[82:85]
	ds_read_b64_tr_b16 v[224:225], v146 offset:32768
	ds_read_b64_tr_b16 v[226:227], v146 offset:36864
	v_mfma_f32_16x16x32_bf16 v[70:73], v[228:231], v[110:113], v[70:73]
	v_cvt_pk_bf16_f32 v203, v206, v207
	v_cvt_pk_bf16_f32 v208, v208, v209
	v_cvt_pk_bf16_f32 v209, v210, v211
	v_mfma_f32_16x16x32_bf16 v[86:89], v[228:231], v[126:129], v[86:89]
	s_waitcnt lgkmcnt(10)
	v_mfma_f32_16x16x32_bf16 v[74:77], v[232:235], v[110:113], v[74:77]
	v_cvt_pk_bf16_f32 v210, v212, v213
	v_cvt_pk_bf16_f32 v211, v214, v215
	v_cvt_pk_bf16_f32 v216, v216, v217
	v_mfma_f32_16x16x32_bf16 v[90:93], v[232:235], v[126:129], v[90:93]
	v_mfma_f32_16x16x32_bf16 v[78:81], v[236:239], v[110:113], v[78:81]
	v_cvt_pk_bf16_f32 v217, v218, v219
	v_cvt_pk_bf16_f32 v218, v220, v221
	v_cvt_pk_bf16_f32 v219, v222, v223
	v_mfma_f32_16x16x32_bf16 v[94:97], v[236:239], v[126:129], v[94:97]
	s_waitcnt lgkmcnt(6)
	v_mfma_f32_16x16x32_bf16 v[2:5], v[192:195], v[166:169], v[2:5]
	v_mfma_f32_16x16x32_bf16 v[34:37], v[208:211], v[166:169], v[34:37]
	ds_read_b64_tr_b16 v[228:229], v147 offset:32768
	ds_read_b64_tr_b16 v[230:231], v147 offset:36864
	v_mfma_f32_16x16x32_bf16 v[6:9], v[192:195], v[170:173], v[6:9]
	v_mfma_f32_16x16x32_bf16 v[38:41], v[208:211], v[170:173], v[38:41]
	ds_read_b64_tr_b16 v[232:233], v148 offset:32768
	ds_read_b64_tr_b16 v[234:235], v148 offset:36864
	s_waitcnt lgkmcnt(6)
	v_mfma_f32_16x16x32_bf16 v[10:13], v[192:195], v[174:177], v[10:13]
	v_exp_f32_e32 v66, v66
	v_exp_f32_e32 v67, v67
	v_exp_f32_e32 v68, v68
	v_mfma_f32_16x16x32_bf16 v[42:45], v[208:211], v[174:177], v[42:45]
	ds_read_b64_tr_b16 v[236:237], v149 offset:32768
	ds_read_b64_tr_b16 v[238:239], v149 offset:36864
	v_mfma_f32_16x16x32_bf16 v[14:17], v[192:195], v[178:181], v[14:17]
	v_exp_f32_e32 v69, v69
	v_exp_f32_e32 v82, v82
	v_mfma_f32_16x16x32_bf16 v[46:49], v[208:211], v[178:181], v[46:49]
	ds_read_b64_tr_b16 v[166:167], v142 offset:40960
	ds_read_b64_tr_b16 v[168:169], v142 offset:45056
	s_waitcnt lgkmcnt(6)
	v_mfma_f32_16x16x32_bf16 v[18:21], v[192:195], v[224:227], v[18:21]
	v_exp_f32_e32 v83, v83
	v_exp_f32_e32 v84, v84
	v_mfma_f32_16x16x32_bf16 v[50:53], v[208:211], v[224:227], v[50:53]
	ds_read_b64_tr_b16 v[170:171], v143 offset:40960
	ds_read_b64_tr_b16 v[172:173], v143 offset:45056
	v_mfma_f32_16x16x32_bf16 v[22:25], v[192:195], v[228:231], v[22:25]
	v_exp_f32_e32 v85, v85
	v_exp_f32_e32 v70, v70
	v_exp_f32_e32 v71, v71
	v_mfma_f32_16x16x32_bf16 v[54:57], v[208:211], v[228:231], v[54:57]
	ds_read_b64_tr_b16 v[174:175], v144 offset:40960
	ds_read_b64_tr_b16 v[176:177], v144 offset:45056
	s_waitcnt lgkmcnt(6)
	v_mfma_f32_16x16x32_bf16 v[26:29], v[192:195], v[232:235], v[26:29]
	v_exp_f32_e32 v72, v72
	v_exp_f32_e32 v73, v73
	v_mfma_f32_16x16x32_bf16 v[58:61], v[208:211], v[232:235], v[58:61]
	ds_read_b64_tr_b16 v[178:179], v145 offset:40960
	ds_read_b64_tr_b16 v[180:181], v145 offset:45056
	v_mfma_f32_16x16x32_bf16 v[30:33], v[192:195], v[236:239], v[30:33]
	v_exp_f32_e32 v86, v86
	v_exp_f32_e32 v87, v87
	v_mfma_f32_16x16x32_bf16 v[62:65], v[208:211], v[236:239], v[62:65]
	ds_read_b64_tr_b16 v[224:225], v146 offset:40960
	ds_read_b64_tr_b16 v[226:227], v146 offset:45056
	s_waitcnt lgkmcnt(6)
	v_mfma_f32_16x16x32_bf16 v[2:5], v[200:203], v[166:169], v[2:5]
	v_exp_f32_e32 v88, v88
	v_exp_f32_e32 v89, v89
	v_mfma_f32_16x16x32_bf16 v[34:37], v[216:219], v[166:169], v[34:37]
	ds_read_b64_tr_b16 v[228:229], v147 offset:40960
	ds_read_b64_tr_b16 v[230:231], v147 offset:45056
	ds_read_b128 v[166:169], v183 offset:49152
	v_mfma_f32_16x16x32_bf16 v[6:9], v[200:203], v[170:173], v[6:9]
	v_exp_f32_e32 v74, v74
	v_exp_f32_e32 v75, v75
	v_exp_f32_e32 v76, v76
	v_mfma_f32_16x16x32_bf16 v[38:41], v[216:219], v[170:173], v[38:41]
	ds_read_b64_tr_b16 v[232:233], v148 offset:40960
	ds_read_b64_tr_b16 v[234:235], v148 offset:45056
	ds_read_b128 v[170:173], v183 offset:53248
	s_waitcnt lgkmcnt(8)
	v_mfma_f32_16x16x32_bf16 v[10:13], v[200:203], v[174:177], v[10:13]
	v_exp_f32_e32 v77, v77
	v_exp_f32_e32 v90, v90
	v_mfma_f32_16x16x32_bf16 v[42:45], v[216:219], v[174:177], v[42:45]
	ds_read_b64_tr_b16 v[236:237], v149 offset:40960
	ds_read_b64_tr_b16 v[238:239], v149 offset:45056
	ds_read_b128 v[174:177], v183 offset:57344
	v_mfma_f32_16x16x32_bf16 v[14:17], v[200:203], v[178:181], v[14:17]
	v_exp_f32_e32 v91, v91
	v_exp_f32_e32 v92, v92
	v_mfma_f32_16x16x32_bf16 v[46:49], v[216:219], v[178:181], v[46:49]
	ds_read_b128 v[178:181], v183 offset:61440
	s_waitcnt lgkmcnt(8)
	v_mfma_f32_16x16x32_bf16 v[18:21], v[200:203], v[224:227], v[18:21]
	v_exp_f32_e32 v93, v93
	v_exp_f32_e32 v78, v78
	v_exp_f32_e32 v79, v79
	v_mfma_f32_16x16x32_bf16 v[50:53], v[216:219], v[224:227], v[50:53]
	ds_read_b128 v[224:227], v184 offset:49152
	v_mfma_f32_16x16x32_bf16 v[22:25], v[200:203], v[228:231], v[22:25]
	v_exp_f32_e32 v80, v80
	v_exp_f32_e32 v81, v81
	v_mfma_f32_16x16x32_bf16 v[54:57], v[216:219], v[228:231], v[54:57]
	ds_read_b128 v[228:231], v184 offset:53248
	s_waitcnt lgkmcnt(4)
	v_mfma_f32_16x16x32_bf16 v[26:29], v[200:203], v[232:235], v[26:29]
	v_exp_f32_e32 v94, v94
	v_exp_f32_e32 v95, v95
	v_mfma_f32_16x16x32_bf16 v[58:61], v[216:219], v[232:235], v[58:61]
	ds_read_b128 v[232:235], v184 offset:57344
	v_mfma_f32_16x16x32_bf16 v[30:33], v[200:203], v[236:239], v[30:33]
	v_exp_f32_e32 v96, v96
	v_exp_f32_e32 v97, v97
	v_mfma_f32_16x16x32_bf16 v[62:65], v[216:219], v[236:239], v[62:65]
	ds_read_b128 v[236:239], v184 offset:61440
	s_waitcnt vmcnt(0)
	s_barrier
	s_sub_u32 s66, s66, 1
	s_cmp_lg_u32 s66, 0
	s_cbranch_scc1 .Lattn_loop
	v_mfma_f32_16x16x32_bf16 v[192:195], v[166:169], v[98:101], 0
	v_add_f32_e32 v130, v66, v67
	v_add_f32_e32 v131, v68, v69
	v_add_f32_e32 v130, v70, v130
	v_mfma_f32_16x16x32_bf16 v[208:211], v[166:169], v[114:117], 0
	ds_read_b128 v[166:169], v185 offset:49152
	s_add_i32 m0, s45, 0x18000
	s_nop 0
	global_load_lds_dwordx4 v152, s[64:65]
	v_mfma_f32_16x16x32_bf16 v[196:199], v[170:173], v[98:101], 0
	v_add_f32_e32 v131, v71, v131
	v_add_f32_e32 v130, v72, v130
	v_add_f32_e32 v131, v73, v131
	v_mfma_f32_16x16x32_bf16 v[212:215], v[170:173], v[114:117], 0
	ds_read_b128 v[170:173], v185 offset:53248
	s_add_i32 m0, s45, 0x1c000
	s_nop 0
	global_load_lds_dwordx4 v150, s[62:63]
	s_waitcnt lgkmcnt(6)
	v_mfma_f32_16x16x32_bf16 v[200:203], v[174:177], v[98:101], 0
	v_add_f32_e32 v130, v74, v130
	v_add_f32_e32 v131, v75, v131
	v_add_f32_e32 v130, v76, v130
	v_mfma_f32_16x16x32_bf16 v[216:219], v[174:177], v[114:117], 0
	ds_read_b128 v[174:177], v185 offset:57344
	s_add_i32 m0, s45, 0x1a000
	s_nop 0
	global_load_lds_dwordx4 v153, s[64:65]
	v_mfma_f32_16x16x32_bf16 v[204:207], v[178:181], v[98:101], 0
	v_add_f32_e32 v131, v77, v131
	v_add_f32_e32 v130, v78, v130
	v_add_f32_e32 v131, v79, v131
	v_mfma_f32_16x16x32_bf16 v[220:223], v[178:181], v[114:117], 0
	ds_read_b128 v[178:181], v185 offset:61440
	s_add_i32 m0, s45, 0x1e000
	s_nop 0
	global_load_lds_dwordx4 v151, s[62:63]
	s_add_u32 s62, s62, 0x4000
	s_addc_u32 s63, s63, 0
	s_add_u32 s64, s64, 0x4000
	s_addc_u32 s65, s65, 0
	s_waitcnt lgkmcnt(6)
	v_mfma_f32_16x16x32_bf16 v[192:195], v[224:227], v[102:105], v[192:195]
	v_add_f32_e32 v130, v80, v130
	v_add_f32_e32 v131, v81, v131
	v_add_f32_e32 v130, v130, v131
	v_mfma_f32_16x16x32_bf16 v[208:211], v[224:227], v[118:121], v[208:211]
	ds_read_b128 v[224:227], v186 offset:49152
	v_mfma_f32_16x16x32_bf16 v[196:199], v[228:231], v[102:105], v[196:199]
	v_add_f32_e32 v165, v165, v130
	v_add_f32_e32 v132, v82, v83
	v_add_f32_e32 v133, v84, v85
	v_mfma_f32_16x16x32_bf16 v[212:215], v[228:231], v[118:121], v[212:215]
	ds_read_b128 v[228:231], v186 offset:53248
	s_waitcnt lgkmcnt(6)
	v_mfma_f32_16x16x32_bf16 v[200:203], v[232:235], v[102:105], v[200:203]
	v_add_f32_e32 v132, v86, v132
	v_add_f32_e32 v133, v87, v133
	v_add_f32_e32 v132, v88, v132
	v_mfma_f32_16x16x32_bf16 v[216:219], v[232:235], v[118:121], v[216:219]
	ds_read_b128 v[232:235], v186 offset:57344
	v_mfma_f32_16x16x32_bf16 v[204:207], v[236:239], v[102:105], v[204:207]
	v_add_f32_e32 v133, v89, v133
	v_add_f32_e32 v132, v90, v132
	v_add_f32_e32 v133, v91, v133
	v_mfma_f32_16x16x32_bf16 v[220:223], v[236:239], v[118:121], v[220:223]
	ds_read_b128 v[236:239], v186 offset:61440
	s_waitcnt lgkmcnt(6)
	v_mfma_f32_16x16x32_bf16 v[192:195], v[166:169], v[106:109], v[192:195]
	v_add_f32_e32 v132, v92, v132
	v_add_f32_e32 v133, v93, v133
	v_add_f32_e32 v132, v94, v132
	v_mfma_f32_16x16x32_bf16 v[208:211], v[166:169], v[122:125], v[208:211]
	ds_read_b64_tr_b16 v[166:167], v240 offset:0
	ds_read_b64_tr_b16 v[168:169], v240 offset:4096
	v_mfma_f32_16x16x32_bf16 v[196:199], v[170:173], v[106:109], v[196:199]
	v_add_f32_e32 v133, v95, v133
	v_add_f32_e32 v132, v96, v132
	v_add_f32_e32 v133, v97, v133
	v_mfma_f32_16x16x32_bf16 v[212:215], v[170:173], v[122:125], v[212:215]
	ds_read_b64_tr_b16 v[170:171], v241 offset:0
	ds_read_b64_tr_b16 v[172:173], v241 offset:4096
	s_waitcnt lgkmcnt(8)
	v_mfma_f32_16x16x32_bf16 v[200:203], v[174:177], v[106:109], v[200:203]
	v_add_f32_e32 v132, v132, v133
	v_add_f32_e32 v163, v163, v132
	v_cvt_pk_bf16_f32 v66, v66, v67
	v_mfma_f32_16x16x32_bf16 v[216:219], v[174:177], v[122:125], v[216:219]
	ds_read_b64_tr_b16 v[174:175], v242 offset:0
	ds_read_b64_tr_b16 v[176:177], v242 offset:4096
	v_mfma_f32_16x16x32_bf16 v[204:207], v[178:181], v[106:109], v[204:207]
	v_cvt_pk_bf16_f32 v67, v68, v69
	v_cvt_pk_bf16_f32 v68, v70, v71
	v_cvt_pk_bf16_f32 v69, v72, v73
	v_mfma_f32_16x16x32_bf16 v[220:223], v[178:181], v[122:125], v[220:223]
	ds_read_b64_tr_b16 v[178:179], v243 offset:0
	ds_read_b64_tr_b16 v[180:181], v243 offset:4096
	s_waitcnt lgkmcnt(10)
	v_mfma_f32_16x16x32_bf16 v[192:195], v[224:227], v[110:113], v[192:195]
	v_cvt_pk_bf16_f32 v74, v74, v75
	v_cvt_pk_bf16_f32 v75, v76, v77
	v_cvt_pk_bf16_f32 v76, v78, v79
	v_mfma_f32_16x16x32_bf16 v[208:211], v[224:227], v[126:129], v[208:211]
	ds_read_b64_tr_b16 v[224:225], v244 offset:0
	ds_read_b64_tr_b16 v[226:227], v244 offset:4096
	v_mfma_f32_16x16x32_bf16 v[196:199], v[228:231], v[110:113], v[196:199]
	v_cvt_pk_bf16_f32 v77, v80, v81
	v_cvt_pk_bf16_f32 v82, v82, v83
	v_cvt_pk_bf16_f32 v83, v84, v85
	v_mfma_f32_16x16x32_bf16 v[212:215], v[228:231], v[126:129], v[212:215]
	s_waitcnt lgkmcnt(10)
	v_mfma_f32_16x16x32_bf16 v[200:203], v[232:235], v[110:113], v[200:203]
	v_cvt_pk_bf16_f32 v84, v86, v87
	v_cvt_pk_bf16_f32 v85, v88, v89
	v_cvt_pk_bf16_f32 v90, v90, v91
	v_mfma_f32_16x16x32_bf16 v[216:219], v[232:235], v[126:129], v[216:219]
	v_mfma_f32_16x16x32_bf16 v[204:207], v[236:239], v[110:113], v[204:207]
	v_cvt_pk_bf16_f32 v91, v92, v93
	v_cvt_pk_bf16_f32 v92, v94, v95
	v_cvt_pk_bf16_f32 v93, v96, v97
	v_mfma_f32_16x16x32_bf16 v[220:223], v[236:239], v[126:129], v[220:223]
	s_waitcnt lgkmcnt(6)
	v_mfma_f32_16x16x32_bf16 v[2:5], v[66:69], v[166:169], v[2:5]
	v_mfma_f32_16x16x32_bf16 v[34:37], v[82:85], v[166:169], v[34:37]
	ds_read_b64_tr_b16 v[228:229], v245 offset:0
	ds_read_b64_tr_b16 v[230:231], v245 offset:4096
	v_mfma_f32_16x16x32_bf16 v[6:9], v[66:69], v[170:173], v[6:9]
	v_mfma_f32_16x16x32_bf16 v[38:41], v[82:85], v[170:173], v[38:41]
	ds_read_b64_tr_b16 v[232:233], v246 offset:0
	ds_read_b64_tr_b16 v[234:235], v246 offset:4096
	s_waitcnt lgkmcnt(6)
	v_mfma_f32_16x16x32_bf16 v[10:13], v[66:69], v[174:177], v[10:13]
	v_exp_f32_e32 v192, v192
	v_exp_f32_e32 v193, v193
	v_exp_f32_e32 v194, v194
	v_mfma_f32_16x16x32_bf16 v[42:45], v[82:85], v[174:177], v[42:45]
	ds_read_b64_tr_b16 v[236:237], v247 offset:0
	ds_read_b64_tr_b16 v[238:239], v247 offset:4096
	v_mfma_f32_16x16x32_bf16 v[14:17], v[66:69], v[178:181], v[14:17]
	v_exp_f32_e32 v195, v195
	v_exp_f32_e32 v208, v208
	v_mfma_f32_16x16x32_bf16 v[46:49], v[82:85], v[178:181], v[46:49]
	ds_read_b64_tr_b16 v[166:167], v240 offset:8192
	ds_read_b64_tr_b16 v[168:169], v240 offset:12288
	s_waitcnt lgkmcnt(6)
	v_mfma_f32_16x16x32_bf16 v[18:21], v[66:69], v[224:227], v[18:21]
	v_exp_f32_e32 v209, v209
	v_exp_f32_e32 v210, v210
	v_mfma_f32_16x16x32_bf16 v[50:53], v[82:85], v[224:227], v[50:53]
	ds_read_b64_tr_b16 v[170:171], v241 offset:8192
	ds_read_b64_tr_b16 v[172:173], v241 offset:12288
	v_mfma_f32_16x16x32_bf16 v[22:25], v[66:69], v[228:231], v[22:25]
	v_exp_f32_e32 v211, v211
	v_exp_f32_e32 v196, v196
	v_exp_f32_e32 v197, v197
	v_mfma_f32_16x16x32_bf16 v[54:57], v[82:85], v[228:231], v[54:57]
	ds_read_b64_tr_b16 v[174:175], v242 offset:8192
	ds_read_b64_tr_b16 v[176:177], v242 offset:12288
	s_waitcnt lgkmcnt(6)
	v_mfma_f32_16x16x32_bf16 v[26:29], v[66:69], v[232:235], v[26:29]
	v_exp_f32_e32 v198, v198
	v_exp_f32_e32 v199, v199
	v_mfma_f32_16x16x32_bf16 v[58:61], v[82:85], v[232:235], v[58:61]
	ds_read_b64_tr_b16 v[178:179], v243 offset:8192
	ds_read_b64_tr_b16 v[180:181], v243 offset:12288
	v_mfma_f32_16x16x32_bf16 v[30:33], v[66:69], v[236:239], v[30:33]
	v_exp_f32_e32 v212, v212
	v_exp_f32_e32 v213, v213
	v_mfma_f32_16x16x32_bf16 v[62:65], v[82:85], v[236:239], v[62:65]
	ds_read_b64_tr_b16 v[224:225], v244 offset:8192
	ds_read_b64_tr_b16 v[226:227], v244 offset:12288
	s_waitcnt lgkmcnt(6)
	v_mfma_f32_16x16x32_bf16 v[2:5], v[74:77], v[166:169], v[2:5]
	v_exp_f32_e32 v214, v214
	v_exp_f32_e32 v215, v215
	v_mfma_f32_16x16x32_bf16 v[34:37], v[90:93], v[166:169], v[34:37]
	ds_read_b64_tr_b16 v[228:229], v245 offset:8192
	ds_read_b64_tr_b16 v[230:231], v245 offset:12288
	ds_read_b128 v[166:169], v187 offset:16384
	v_mfma_f32_16x16x32_bf16 v[6:9], v[74:77], v[170:173], v[6:9]
	v_exp_f32_e32 v200, v200
	v_exp_f32_e32 v201, v201
	v_exp_f32_e32 v202, v202
	v_mfma_f32_16x16x32_bf16 v[38:41], v[90:93], v[170:173], v[38:41]
	ds_read_b64_tr_b16 v[232:233], v246 offset:8192
	ds_read_b64_tr_b16 v[234:235], v246 offset:12288
	ds_read_b128 v[170:173], v187 offset:20480
	s_waitcnt lgkmcnt(8)
	v_mfma_f32_16x16x32_bf16 v[10:13], v[74:77], v[174:177], v[10:13]
	v_exp_f32_e32 v203, v203
	v_exp_f32_e32 v216, v216
	v_mfma_f32_16x16x32_bf16 v[42:45], v[90:93], v[174:177], v[42:45]
	ds_read_b64_tr_b16 v[236:237], v247 offset:8192
	ds_read_b64_tr_b16 v[238:239], v247 offset:12288
	ds_read_b128 v[174:177], v187 offset:24576
	v_mfma_f32_16x16x32_bf16 v[14:17], v[74:77], v[178:181], v[14:17]
	v_exp_f32_e32 v217, v217
	v_exp_f32_e32 v218, v218
	v_mfma_f32_16x16x32_bf16 v[46:49], v[90:93], v[178:181], v[46:49]
	ds_read_b128 v[178:181], v187 offset:28672
	s_waitcnt lgkmcnt(8)
	v_mfma_f32_16x16x32_bf16 v[18:21], v[74:77], v[224:227], v[18:21]
	v_exp_f32_e32 v219, v219
	v_exp_f32_e32 v204, v204
	v_exp_f32_e32 v205, v205
	v_mfma_f32_16x16x32_bf16 v[50:53], v[90:93], v[224:227], v[50:53]
	ds_read_b128 v[224:227], v188 offset:16384
	v_mfma_f32_16x16x32_bf16 v[22:25], v[74:77], v[228:231], v[22:25]
	v_exp_f32_e32 v206, v206
	v_exp_f32_e32 v207, v207
	v_mfma_f32_16x16x32_bf16 v[54:57], v[90:93], v[228:231], v[54:57]
	ds_read_b128 v[228:231], v188 offset:20480
	s_waitcnt lgkmcnt(4)
	v_mfma_f32_16x16x32_bf16 v[26:29], v[74:77], v[232:235], v[26:29]
	v_exp_f32_e32 v220, v220
	v_exp_f32_e32 v221, v221
	v_mfma_f32_16x16x32_bf16 v[58:61], v[90:93], v[232:235], v[58:61]
	ds_read_b128 v[232:235], v188 offset:24576
	v_mfma_f32_16x16x32_bf16 v[30:33], v[74:77], v[236:239], v[30:33]
	v_exp_f32_e32 v222, v222
	v_exp_f32_e32 v223, v223
	v_mfma_f32_16x16x32_bf16 v[62:65], v[90:93], v[236:239], v[62:65]
	ds_read_b128 v[236:239], v188 offset:28672
	s_waitcnt vmcnt(0)
	s_barrier
	s_add_i32 s66, s3, s33
	s_cmpk_lt_i32 s66, 0x400
	s_cselect_b32 s66, s66, s3
	s_lshr_b32 s0, s66, 7
	s_lshl_b32 s0, s0, 23
	s_and_b32 s1, s66, 15
	s_lshl_b32 s1, s1, 19
	s_or_b32 s0, s0, s1
	s_bfe_u32 s1, s66, 0x30004
	s_lshl_b32 s1, s1, 8
	s_or_b32 s0, s0, s1
	s_add_u32 s60, s25, s0
	s_addc_u32 s61, s28, 0
	s_add_u32 s18, s21, s0
	s_addc_u32 s19, s24, 0
	s_lshr_b32 s1, s66, 6
	s_mul_i32 s1, s1, 0x110000
	s_add_u32 s62, s9, s1
	s_addc_u32 s63, s20, 0
	s_add_u32 s64, s29, s1
	s_addc_u32 s65, s30, 0
	v_mfma_f32_16x16x32_bf16 v[66:69], v[166:169], v[98:101], 0
	v_add_f32_e32 v130, v192, v193
	v_add_f32_e32 v131, v194, v195
	v_add_f32_e32 v130, v196, v130
	v_mfma_f32_16x16x32_bf16 v[82:85], v[166:169], v[114:117], 0
	ds_read_b128 v[166:169], v189 offset:16384
	v_mfma_f32_16x16x32_bf16 v[70:73], v[170:173], v[98:101], 0
	v_add_f32_e32 v131, v197, v131
	v_add_f32_e32 v130, v198, v130
	v_add_f32_e32 v131, v199, v131
	v_mfma_f32_16x16x32_bf16 v[86:89], v[170:173], v[114:117], 0
	ds_read_b128 v[170:173], v189 offset:20480
	s_waitcnt lgkmcnt(6)
	v_mfma_f32_16x16x32_bf16 v[74:77], v[174:177], v[98:101], 0
	v_add_f32_e32 v130, v200, v130
	v_add_f32_e32 v131, v201, v131
	v_add_f32_e32 v130, v202, v130
	v_mfma_f32_16x16x32_bf16 v[90:93], v[174:177], v[114:117], 0
	ds_read_b128 v[174:177], v189 offset:24576
	v_mfma_f32_16x16x32_bf16 v[78:81], v[178:181], v[98:101], 0
	v_add_f32_e32 v131, v203, v131
	v_add_f32_e32 v130, v204, v130
	v_add_f32_e32 v131, v205, v131
	v_mfma_f32_16x16x32_bf16 v[94:97], v[178:181], v[114:117], 0
	ds_read_b128 v[178:181], v189 offset:28672
	s_waitcnt lgkmcnt(6)
	v_mfma_f32_16x16x32_bf16 v[66:69], v[224:227], v[102:105], v[66:69]
	v_add_f32_e32 v130, v206, v130
	v_add_f32_e32 v131, v207, v131
	v_add_f32_e32 v130, v130, v131
	v_mfma_f32_16x16x32_bf16 v[82:85], v[224:227], v[118:121], v[82:85]
	ds_read_b128 v[224:227], v190 offset:16384
	v_mfma_f32_16x16x32_bf16 v[70:73], v[228:231], v[102:105], v[70:73]
	v_add_f32_e32 v165, v165, v130
	v_add_f32_e32 v132, v208, v209
	v_add_f32_e32 v133, v210, v211
	v_mfma_f32_16x16x32_bf16 v[86:89], v[228:231], v[118:121], v[86:89]
	ds_read_b128 v[228:231], v190 offset:20480
	s_waitcnt lgkmcnt(6)
	v_mfma_f32_16x16x32_bf16 v[74:77], v[232:235], v[102:105], v[74:77]
	v_add_f32_e32 v132, v212, v132
	v_add_f32_e32 v133, v213, v133
	v_add_f32_e32 v132, v214, v132
	v_mfma_f32_16x16x32_bf16 v[90:93], v[232:235], v[118:121], v[90:93]
	ds_read_b128 v[232:235], v190 offset:24576
	v_mfma_f32_16x16x32_bf16 v[78:81], v[236:239], v[102:105], v[78:81]
	v_add_f32_e32 v133, v215, v133
	v_add_f32_e32 v132, v216, v132
	v_add_f32_e32 v133, v217, v133
	v_mfma_f32_16x16x32_bf16 v[94:97], v[236:239], v[118:121], v[94:97]
	ds_read_b128 v[236:239], v190 offset:28672
	s_waitcnt lgkmcnt(6)
	v_mfma_f32_16x16x32_bf16 v[66:69], v[166:169], v[106:109], v[66:69]
	v_add_f32_e32 v132, v218, v132
	v_add_f32_e32 v133, v219, v133
	v_add_f32_e32 v132, v220, v132
	v_mfma_f32_16x16x32_bf16 v[82:85], v[166:169], v[122:125], v[82:85]
	ds_read_b64_tr_b16 v[166:167], v240 offset:32768
	ds_read_b64_tr_b16 v[168:169], v240 offset:36864
	v_mfma_f32_16x16x32_bf16 v[70:73], v[170:173], v[106:109], v[70:73]
	v_add_f32_e32 v133, v221, v133
	v_add_f32_e32 v132, v222, v132
	v_add_f32_e32 v133, v223, v133
	v_mfma_f32_16x16x32_bf16 v[86:89], v[170:173], v[122:125], v[86:89]
	ds_read_b64_tr_b16 v[170:171], v241 offset:32768
	ds_read_b64_tr_b16 v[172:173], v241 offset:36864
	s_waitcnt lgkmcnt(8)
	v_mfma_f32_16x16x32_bf16 v[74:77], v[174:177], v[106:109], v[74:77]
	v_add_f32_e32 v132, v132, v133
	v_add_f32_e32 v163, v163, v132
	v_cvt_pk_bf16_f32 v192, v192, v193
	v_mfma_f32_16x16x32_bf16 v[90:93], v[174:177], v[122:125], v[90:93]
	ds_read_b64_tr_b16 v[174:175], v242 offset:32768
	ds_read_b64_tr_b16 v[176:177], v242 offset:36864
	v_mfma_f32_16x16x32_bf16 v[78:81], v[178:181], v[106:109], v[78:81]
	v_cvt_pk_bf16_f32 v193, v194, v195
	v_cvt_pk_bf16_f32 v194, v196, v197
	v_cvt_pk_bf16_f32 v195, v198, v199
	v_mfma_f32_16x16x32_bf16 v[94:97], v[178:181], v[122:125], v[94:97]
	ds_read_b64_tr_b16 v[178:179], v243 offset:32768
	ds_read_b64_tr_b16 v[180:181], v243 offset:36864
	s_waitcnt lgkmcnt(10)
	v_mfma_f32_16x16x32_bf16 v[66:69], v[224:227], v[110:113], v[66:69]
	v_cvt_pk_bf16_f32 v200, v200, v201
	v_cvt_pk_bf16_f32 v201, v202, v203
	v_cvt_pk_bf16_f32 v202, v204, v205
	v_mfma_f32_16x16x32_bf16 v[82:85], v[224:227], v[126:129], v[82:85]
	ds_read_b64_tr_b16 v[224:225], v244 offset:32768
	ds_read_b64_tr_b16 v[226:227], v244 offset:36864
	v_mfma_f32_16x16x32_bf16 v[70:73], v[228:231], v[110:113], v[70:73]
	v_cvt_pk_bf16_f32 v203, v206, v207
	v_cvt_pk_bf16_f32 v208, v208, v209
	v_cvt_pk_bf16_f32 v209, v210, v211
	v_mfma_f32_16x16x32_bf16 v[86:89], v[228:231], v[126:129], v[86:89]
	s_waitcnt lgkmcnt(10)
	v_mfma_f32_16x16x32_bf16 v[74:77], v[232:235], v[110:113], v[74:77]
	v_cvt_pk_bf16_f32 v210, v212, v213
	v_cvt_pk_bf16_f32 v211, v214, v215
	v_cvt_pk_bf16_f32 v216, v216, v217
	v_mfma_f32_16x16x32_bf16 v[90:93], v[232:235], v[126:129], v[90:93]
	v_mfma_f32_16x16x32_bf16 v[78:81], v[236:239], v[110:113], v[78:81]
	v_cvt_pk_bf16_f32 v217, v218, v219
	v_cvt_pk_bf16_f32 v218, v220, v221
	v_cvt_pk_bf16_f32 v219, v222, v223
	v_mfma_f32_16x16x32_bf16 v[94:97], v[236:239], v[126:129], v[94:97]
	s_waitcnt lgkmcnt(6)
	v_mfma_f32_16x16x32_bf16 v[2:5], v[192:195], v[166:169], v[2:5]
	v_mfma_f32_16x16x32_bf16 v[34:37], v[208:211], v[166:169], v[34:37]
	ds_read_b64_tr_b16 v[228:229], v245 offset:32768
	ds_read_b64_tr_b16 v[230:231], v245 offset:36864
	v_mfma_f32_16x16x32_bf16 v[6:9], v[192:195], v[170:173], v[6:9]
	v_mfma_f32_16x16x32_bf16 v[38:41], v[208:211], v[170:173], v[38:41]
	ds_read_b64_tr_b16 v[232:233], v246 offset:32768
	ds_read_b64_tr_b16 v[234:235], v246 offset:36864
	s_waitcnt lgkmcnt(6)
	v_mfma_f32_16x16x32_bf16 v[10:13], v[192:195], v[174:177], v[10:13]
	v_exp_f32_e32 v66, v66
	v_exp_f32_e32 v67, v67
	v_exp_f32_e32 v68, v68
	v_mfma_f32_16x16x32_bf16 v[42:45], v[208:211], v[174:177], v[42:45]
	ds_read_b64_tr_b16 v[236:237], v247 offset:32768
	ds_read_b64_tr_b16 v[238:239], v247 offset:36864
	v_mfma_f32_16x16x32_bf16 v[14:17], v[192:195], v[178:181], v[14:17]
	v_exp_f32_e32 v69, v69
	v_exp_f32_e32 v82, v82
	v_mfma_f32_16x16x32_bf16 v[46:49], v[208:211], v[178:181], v[46:49]
	ds_read_b64_tr_b16 v[166:167], v240 offset:40960
	ds_read_b64_tr_b16 v[168:169], v240 offset:45056
	s_waitcnt lgkmcnt(6)
	v_mfma_f32_16x16x32_bf16 v[18:21], v[192:195], v[224:227], v[18:21]
	v_exp_f32_e32 v83, v83
	v_exp_f32_e32 v84, v84
	v_mfma_f32_16x16x32_bf16 v[50:53], v[208:211], v[224:227], v[50:53]
	ds_read_b64_tr_b16 v[170:171], v241 offset:40960
	ds_read_b64_tr_b16 v[172:173], v241 offset:45056
	v_mfma_f32_16x16x32_bf16 v[22:25], v[192:195], v[228:231], v[22:25]
	v_exp_f32_e32 v85, v85
	v_exp_f32_e32 v70, v70
	v_exp_f32_e32 v71, v71
	v_mfma_f32_16x16x32_bf16 v[54:57], v[208:211], v[228:231], v[54:57]
	ds_read_b64_tr_b16 v[174:175], v242 offset:40960
	ds_read_b64_tr_b16 v[176:177], v242 offset:45056
	s_waitcnt lgkmcnt(6)
	v_mfma_f32_16x16x32_bf16 v[26:29], v[192:195], v[232:235], v[26:29]
	v_exp_f32_e32 v72, v72
	v_exp_f32_e32 v73, v73
	v_mfma_f32_16x16x32_bf16 v[58:61], v[208:211], v[232:235], v[58:61]
	ds_read_b64_tr_b16 v[178:179], v243 offset:40960
	ds_read_b64_tr_b16 v[180:181], v243 offset:45056
	v_mfma_f32_16x16x32_bf16 v[30:33], v[192:195], v[236:239], v[30:33]
	v_exp_f32_e32 v86, v86
	v_exp_f32_e32 v87, v87
	v_mfma_f32_16x16x32_bf16 v[62:65], v[208:211], v[236:239], v[62:65]
	ds_read_b64_tr_b16 v[224:225], v244 offset:40960
	ds_read_b64_tr_b16 v[226:227], v244 offset:45056
	s_waitcnt lgkmcnt(6)
	v_mfma_f32_16x16x32_bf16 v[2:5], v[200:203], v[166:169], v[2:5]
	v_exp_f32_e32 v88, v88
	v_exp_f32_e32 v89, v89
	v_mfma_f32_16x16x32_bf16 v[34:37], v[216:219], v[166:169], v[34:37]
	ds_read_b64_tr_b16 v[228:229], v245 offset:40960
	ds_read_b64_tr_b16 v[230:231], v245 offset:45056
	ds_read_b128 v[166:169], v187 offset:49152
	v_mfma_f32_16x16x32_bf16 v[6:9], v[200:203], v[170:173], v[6:9]
	v_exp_f32_e32 v74, v74
	v_exp_f32_e32 v75, v75
	v_exp_f32_e32 v76, v76
	v_mfma_f32_16x16x32_bf16 v[38:41], v[216:219], v[170:173], v[38:41]
	ds_read_b64_tr_b16 v[232:233], v246 offset:40960
	ds_read_b64_tr_b16 v[234:235], v246 offset:45056
	ds_read_b128 v[170:173], v187 offset:53248
	s_waitcnt lgkmcnt(8)
	v_mfma_f32_16x16x32_bf16 v[10:13], v[200:203], v[174:177], v[10:13]
	v_exp_f32_e32 v77, v77
	v_exp_f32_e32 v90, v90
	v_mfma_f32_16x16x32_bf16 v[42:45], v[216:219], v[174:177], v[42:45]
	ds_read_b64_tr_b16 v[236:237], v247 offset:40960
	ds_read_b64_tr_b16 v[238:239], v247 offset:45056
	ds_read_b128 v[174:177], v187 offset:57344
	v_mfma_f32_16x16x32_bf16 v[14:17], v[200:203], v[178:181], v[14:17]
	v_exp_f32_e32 v91, v91
	v_exp_f32_e32 v92, v92
	v_mfma_f32_16x16x32_bf16 v[46:49], v[216:219], v[178:181], v[46:49]
	ds_read_b128 v[178:181], v187 offset:61440
	s_waitcnt lgkmcnt(8)
	v_mfma_f32_16x16x32_bf16 v[18:21], v[200:203], v[224:227], v[18:21]
	v_exp_f32_e32 v93, v93
	v_exp_f32_e32 v78, v78
	v_exp_f32_e32 v79, v79
	v_mfma_f32_16x16x32_bf16 v[50:53], v[216:219], v[224:227], v[50:53]
	ds_read_b128 v[224:227], v188 offset:49152
	v_mfma_f32_16x16x32_bf16 v[22:25], v[200:203], v[228:231], v[22:25]
	v_exp_f32_e32 v80, v80
	v_exp_f32_e32 v81, v81
	v_mfma_f32_16x16x32_bf16 v[54:57], v[216:219], v[228:231], v[54:57]
	ds_read_b128 v[228:231], v188 offset:53248
	s_waitcnt lgkmcnt(4)
	v_mfma_f32_16x16x32_bf16 v[26:29], v[200:203], v[232:235], v[26:29]
	v_exp_f32_e32 v94, v94
	v_exp_f32_e32 v95, v95
	v_mfma_f32_16x16x32_bf16 v[58:61], v[216:219], v[232:235], v[58:61]
	ds_read_b128 v[232:235], v188 offset:57344
	v_mfma_f32_16x16x32_bf16 v[30:33], v[200:203], v[236:239], v[30:33]
	v_exp_f32_e32 v96, v96
	v_exp_f32_e32 v97, v97
	v_mfma_f32_16x16x32_bf16 v[62:65], v[216:219], v[236:239], v[62:65]
	ds_read_b128 v[236:239], v188 offset:61440
	s_barrier
	v_mfma_f32_16x16x32_bf16 v[192:195], v[166:169], v[98:101], 0
	v_add_f32_e32 v130, v66, v67
	v_add_f32_e32 v131, v68, v69
	v_add_f32_e32 v130, v70, v130
	v_mfma_f32_16x16x32_bf16 v[208:211], v[166:169], v[114:117], 0
	ds_read_b128 v[166:169], v189 offset:49152
	s_add_i32 m0, s45, 0x0
	s_nop 0
	global_load_lds_dwordx4 v152, s[64:65]
	v_mfma_f32_16x16x32_bf16 v[196:199], v[170:173], v[98:101], 0
	v_add_f32_e32 v131, v71, v131
	v_add_f32_e32 v130, v72, v130
	v_add_f32_e32 v131, v73, v131
	v_mfma_f32_16x16x32_bf16 v[212:215], v[170:173], v[114:117], 0
	ds_read_b128 v[170:173], v189 offset:53248
	s_add_i32 m0, s45, 0x4000
	s_nop 0
	global_load_lds_dwordx4 v150, s[62:63]
	s_waitcnt lgkmcnt(6)
	v_mfma_f32_16x16x32_bf16 v[200:203], v[174:177], v[98:101], 0
	v_add_f32_e32 v130, v74, v130
	v_add_f32_e32 v131, v75, v131
	v_add_f32_e32 v130, v76, v130
	v_mfma_f32_16x16x32_bf16 v[216:219], v[174:177], v[114:117], 0
	ds_read_b128 v[174:177], v189 offset:57344
	s_add_i32 m0, s45, 0x2000
	s_nop 0
	global_load_lds_dwordx4 v153, s[64:65]
	v_mfma_f32_16x16x32_bf16 v[204:207], v[178:181], v[98:101], 0
	v_add_f32_e32 v131, v77, v131
	v_add_f32_e32 v130, v78, v130
	v_add_f32_e32 v131, v79, v131
	v_mfma_f32_16x16x32_bf16 v[220:223], v[178:181], v[114:117], 0
	ds_read_b128 v[178:181], v189 offset:61440
	s_add_i32 m0, s45, 0x6000
	s_nop 0
	global_load_lds_dwordx4 v151, s[62:63]
	s_add_u32 s62, s62, 0x4000
	s_addc_u32 s63, s63, 0
	s_add_u32 s64, s64, 0x4000
	s_addc_u32 s65, s65, 0
	s_waitcnt lgkmcnt(6)
	v_mfma_f32_16x16x32_bf16 v[192:195], v[224:227], v[102:105], v[192:195]
	v_add_f32_e32 v130, v80, v130
	v_add_f32_e32 v131, v81, v131
	v_add_f32_e32 v130, v130, v131
	v_mfma_f32_16x16x32_bf16 v[208:211], v[224:227], v[118:121], v[208:211]
	ds_read_b128 v[224:227], v190 offset:49152
	v_mfma_f32_16x16x32_bf16 v[196:199], v[228:231], v[102:105], v[196:199]
	v_add_f32_e32 v165, v165, v130
	v_add_f32_e32 v132, v82, v83
	v_add_f32_e32 v133, v84, v85
	v_mfma_f32_16x16x32_bf16 v[212:215], v[228:231], v[118:121], v[212:215]
	ds_read_b128 v[228:231], v190 offset:53248
	s_waitcnt lgkmcnt(6)
	v_mfma_f32_16x16x32_bf16 v[200:203], v[232:235], v[102:105], v[200:203]
	v_add_f32_e32 v132, v86, v132
	v_add_f32_e32 v133, v87, v133
	v_add_f32_e32 v132, v88, v132
	v_mfma_f32_16x16x32_bf16 v[216:219], v[232:235], v[118:121], v[216:219]
	ds_read_b128 v[232:235], v190 offset:57344
	v_mfma_f32_16x16x32_bf16 v[204:207], v[236:239], v[102:105], v[204:207]
	v_add_f32_e32 v133, v89, v133
	v_add_f32_e32 v132, v90, v132
	v_add_f32_e32 v133, v91, v133
	v_mfma_f32_16x16x32_bf16 v[220:223], v[236:239], v[118:121], v[220:223]
	ds_read_b128 v[236:239], v190 offset:61440
	s_waitcnt lgkmcnt(6)
	v_mfma_f32_16x16x32_bf16 v[192:195], v[166:169], v[106:109], v[192:195]
	v_add_f32_e32 v132, v92, v132
	v_add_f32_e32 v133, v93, v133
	v_add_f32_e32 v132, v94, v132
	v_mfma_f32_16x16x32_bf16 v[208:211], v[166:169], v[122:125], v[208:211]
	ds_read_b64_tr_b16 v[166:167], v142 offset:0
	ds_read_b64_tr_b16 v[168:169], v142 offset:4096
	v_mfma_f32_16x16x32_bf16 v[196:199], v[170:173], v[106:109], v[196:199]
	v_add_f32_e32 v133, v95, v133
	v_add_f32_e32 v132, v96, v132
	v_add_f32_e32 v133, v97, v133
	v_mfma_f32_16x16x32_bf16 v[212:215], v[170:173], v[122:125], v[212:215]
	ds_read_b64_tr_b16 v[170:171], v143 offset:0
	ds_read_b64_tr_b16 v[172:173], v143 offset:4096
	s_waitcnt lgkmcnt(8)
	v_mfma_f32_16x16x32_bf16 v[200:203], v[174:177], v[106:109], v[200:203]
	v_add_f32_e32 v132, v132, v133
	v_add_f32_e32 v163, v163, v132
	v_cvt_pk_bf16_f32 v66, v66, v67
	v_mfma_f32_16x16x32_bf16 v[216:219], v[174:177], v[122:125], v[216:219]
	ds_read_b64_tr_b16 v[174:175], v144 offset:0
	ds_read_b64_tr_b16 v[176:177], v144 offset:4096
	v_mfma_f32_16x16x32_bf16 v[204:207], v[178:181], v[106:109], v[204:207]
	v_cvt_pk_bf16_f32 v67, v68, v69
	v_cvt_pk_bf16_f32 v68, v70, v71
	v_cvt_pk_bf16_f32 v69, v72, v73
	v_mfma_f32_16x16x32_bf16 v[220:223], v[178:181], v[122:125], v[220:223]
	ds_read_b64_tr_b16 v[178:179], v145 offset:0
	ds_read_b64_tr_b16 v[180:181], v145 offset:4096
	s_waitcnt lgkmcnt(10)
	v_mfma_f32_16x16x32_bf16 v[192:195], v[224:227], v[110:113], v[192:195]
	v_cvt_pk_bf16_f32 v74, v74, v75
	v_cvt_pk_bf16_f32 v75, v76, v77
	v_cvt_pk_bf16_f32 v76, v78, v79
	v_mfma_f32_16x16x32_bf16 v[208:211], v[224:227], v[126:129], v[208:211]
	ds_read_b64_tr_b16 v[224:225], v146 offset:0
	ds_read_b64_tr_b16 v[226:227], v146 offset:4096
	v_mfma_f32_16x16x32_bf16 v[196:199], v[228:231], v[110:113], v[196:199]
	v_cvt_pk_bf16_f32 v77, v80, v81
	v_cvt_pk_bf16_f32 v82, v82, v83
	v_cvt_pk_bf16_f32 v83, v84, v85
	v_mfma_f32_16x16x32_bf16 v[212:215], v[228:231], v[126:129], v[212:215]
	s_waitcnt lgkmcnt(10)
	v_mfma_f32_16x16x32_bf16 v[200:203], v[232:235], v[110:113], v[200:203]
	v_cvt_pk_bf16_f32 v84, v86, v87
	v_cvt_pk_bf16_f32 v85, v88, v89
	v_cvt_pk_bf16_f32 v90, v90, v91
	v_mfma_f32_16x16x32_bf16 v[216:219], v[232:235], v[126:129], v[216:219]
	v_mfma_f32_16x16x32_bf16 v[204:207], v[236:239], v[110:113], v[204:207]
	v_cvt_pk_bf16_f32 v91, v92, v93
	v_cvt_pk_bf16_f32 v92, v94, v95
	v_cvt_pk_bf16_f32 v93, v96, v97
	v_mfma_f32_16x16x32_bf16 v[220:223], v[236:239], v[126:129], v[220:223]
	s_waitcnt lgkmcnt(6)
	v_mfma_f32_16x16x32_bf16 v[2:5], v[66:69], v[166:169], v[2:5]
	v_mfma_f32_16x16x32_bf16 v[34:37], v[82:85], v[166:169], v[34:37]
	ds_read_b64_tr_b16 v[228:229], v147 offset:0
	ds_read_b64_tr_b16 v[230:231], v147 offset:4096
	v_mfma_f32_16x16x32_bf16 v[6:9], v[66:69], v[170:173], v[6:9]
	v_mfma_f32_16x16x32_bf16 v[38:41], v[82:85], v[170:173], v[38:41]
	ds_read_b64_tr_b16 v[232:233], v148 offset:0
	ds_read_b64_tr_b16 v[234:235], v148 offset:4096
	s_waitcnt lgkmcnt(6)
	v_mfma_f32_16x16x32_bf16 v[10:13], v[66:69], v[174:177], v[10:13]
	v_exp_f32_e32 v192, v192
	v_exp_f32_e32 v193, v193
	v_exp_f32_e32 v194, v194
	v_mfma_f32_16x16x32_bf16 v[42:45], v[82:85], v[174:177], v[42:45]
	ds_read_b64_tr_b16 v[236:237], v149 offset:0
	ds_read_b64_tr_b16 v[238:239], v149 offset:4096
	v_mfma_f32_16x16x32_bf16 v[14:17], v[66:69], v[178:181], v[14:17]
	v_exp_f32_e32 v195, v195
	v_exp_f32_e32 v208, v208
	v_mfma_f32_16x16x32_bf16 v[46:49], v[82:85], v[178:181], v[46:49]
	ds_read_b64_tr_b16 v[166:167], v142 offset:8192
	ds_read_b64_tr_b16 v[168:169], v142 offset:12288
	s_waitcnt lgkmcnt(6)
	v_mfma_f32_16x16x32_bf16 v[18:21], v[66:69], v[224:227], v[18:21]
	v_exp_f32_e32 v209, v209
	v_exp_f32_e32 v210, v210
	v_mfma_f32_16x16x32_bf16 v[50:53], v[82:85], v[224:227], v[50:53]
	ds_read_b64_tr_b16 v[170:171], v143 offset:8192
	ds_read_b64_tr_b16 v[172:173], v143 offset:12288
	v_mfma_f32_16x16x32_bf16 v[22:25], v[66:69], v[228:231], v[22:25]
	v_exp_f32_e32 v211, v211
	v_exp_f32_e32 v196, v196
	v_exp_f32_e32 v197, v197
	v_mfma_f32_16x16x32_bf16 v[54:57], v[82:85], v[228:231], v[54:57]
	ds_read_b64_tr_b16 v[174:175], v144 offset:8192
	ds_read_b64_tr_b16 v[176:177], v144 offset:12288
	s_waitcnt lgkmcnt(6)
	v_mfma_f32_16x16x32_bf16 v[26:29], v[66:69], v[232:235], v[26:29]
	v_exp_f32_e32 v198, v198
	v_exp_f32_e32 v199, v199
	v_mfma_f32_16x16x32_bf16 v[58:61], v[82:85], v[232:235], v[58:61]
	ds_read_b64_tr_b16 v[178:179], v145 offset:8192
	ds_read_b64_tr_b16 v[180:181], v145 offset:12288
	v_mfma_f32_16x16x32_bf16 v[30:33], v[66:69], v[236:239], v[30:33]
	v_exp_f32_e32 v212, v212
	v_exp_f32_e32 v213, v213
	v_mfma_f32_16x16x32_bf16 v[62:65], v[82:85], v[236:239], v[62:65]
	ds_read_b64_tr_b16 v[224:225], v146 offset:8192
	ds_read_b64_tr_b16 v[226:227], v146 offset:12288
	s_waitcnt lgkmcnt(6)
	v_mfma_f32_16x16x32_bf16 v[2:5], v[74:77], v[166:169], v[2:5]
	v_exp_f32_e32 v214, v214
	v_exp_f32_e32 v215, v215
	v_mfma_f32_16x16x32_bf16 v[34:37], v[90:93], v[166:169], v[34:37]
	ds_read_b64_tr_b16 v[228:229], v147 offset:8192
	ds_read_b64_tr_b16 v[230:231], v147 offset:12288
	v_mfma_f32_16x16x32_bf16 v[6:9], v[74:77], v[170:173], v[6:9]
	v_exp_f32_e32 v200, v200
	v_exp_f32_e32 v201, v201
	v_exp_f32_e32 v202, v202
	v_mfma_f32_16x16x32_bf16 v[38:41], v[90:93], v[170:173], v[38:41]
	ds_read_b64_tr_b16 v[232:233], v148 offset:8192
	ds_read_b64_tr_b16 v[234:235], v148 offset:12288
	s_waitcnt lgkmcnt(6)
	v_mfma_f32_16x16x32_bf16 v[10:13], v[74:77], v[174:177], v[10:13]
	v_exp_f32_e32 v203, v203
	v_exp_f32_e32 v216, v216
	v_mfma_f32_16x16x32_bf16 v[42:45], v[90:93], v[174:177], v[42:45]
	ds_read_b64_tr_b16 v[236:237], v149 offset:8192
	ds_read_b64_tr_b16 v[238:239], v149 offset:12288
	v_mfma_f32_16x16x32_bf16 v[14:17], v[74:77], v[178:181], v[14:17]
	v_exp_f32_e32 v217, v217
	v_exp_f32_e32 v218, v218
	v_mfma_f32_16x16x32_bf16 v[46:49], v[90:93], v[178:181], v[46:49]
	s_waitcnt lgkmcnt(4)
	v_mfma_f32_16x16x32_bf16 v[18:21], v[74:77], v[224:227], v[18:21]
	v_exp_f32_e32 v219, v219
	v_exp_f32_e32 v204, v204
	v_exp_f32_e32 v205, v205
	v_mfma_f32_16x16x32_bf16 v[50:53], v[90:93], v[224:227], v[50:53]
	v_mfma_f32_16x16x32_bf16 v[22:25], v[74:77], v[228:231], v[22:25]
	v_exp_f32_e32 v206, v206
	v_exp_f32_e32 v207, v207
	v_mfma_f32_16x16x32_bf16 v[54:57], v[90:93], v[228:231], v[54:57]
	s_waitcnt lgkmcnt(0)
	v_mfma_f32_16x16x32_bf16 v[26:29], v[74:77], v[232:235], v[26:29]
	v_exp_f32_e32 v220, v220
	v_exp_f32_e32 v221, v221
	v_mfma_f32_16x16x32_bf16 v[58:61], v[90:93], v[232:235], v[58:61]
	v_mfma_f32_16x16x32_bf16 v[30:33], v[74:77], v[236:239], v[30:33]
	v_exp_f32_e32 v222, v222
	v_exp_f32_e32 v223, v223
	v_mfma_f32_16x16x32_bf16 v[62:65], v[90:93], v[236:239], v[62:65]
	s_add_i32 m0, s45, 0x8000
	s_nop 0
	global_load_lds_dwordx4 v152, s[64:65]
	s_add_i32 m0, s45, 0xc000
	s_nop 0
	global_load_lds_dwordx4 v150, s[62:63]
	s_add_i32 m0, s45, 0xa000
	s_nop 0
	global_load_lds_dwordx4 v153, s[64:65]
	s_add_i32 m0, s45, 0xe000
	s_nop 0
	global_load_lds_dwordx4 v151, s[62:63]
	s_add_u32 s62, s62, 0x4000
	s_addc_u32 s63, s63, 0
	s_add_u32 s64, s64, 0x4000
	s_addc_u32 s65, s65, 0
	global_load_dwordx4 v[98:101], v154, s[60:61]
	global_load_dwordx4 v[102:105], v154, s[60:61] offset:64
	global_load_dwordx4 v[106:109], v154, s[60:61] offset:128
	global_load_dwordx4 v[110:113], v154, s[60:61] offset:192
	global_load_dwordx4 v[114:117], v155, s[60:61]
	global_load_dwordx4 v[118:121], v155, s[60:61] offset:64
	global_load_dwordx4 v[122:125], v155, s[60:61] offset:128
	global_load_dwordx4 v[126:129], v155, s[60:61] offset:192
	s_barrier
	ds_read_b64_tr_b16 v[166:167], v142 offset:32768
	ds_read_b64_tr_b16 v[168:169], v142 offset:36864
	ds_read_b64_tr_b16 v[170:171], v143 offset:32768
	ds_read_b64_tr_b16 v[172:173], v143 offset:36864
	ds_read_b64_tr_b16 v[174:175], v144 offset:32768
	ds_read_b64_tr_b16 v[176:177], v144 offset:36864
	ds_read_b64_tr_b16 v[178:179], v145 offset:32768
	ds_read_b64_tr_b16 v[180:181], v145 offset:36864
	ds_read_b64_tr_b16 v[224:225], v146 offset:32768
	ds_read_b64_tr_b16 v[226:227], v146 offset:36864
	v_add_f32_e32 v130, v192, v193
	v_add_f32_e32 v131, v194, v195
	v_add_f32_e32 v130, v196, v130
	v_add_f32_e32 v131, v197, v131
	v_add_f32_e32 v130, v198, v130
	v_add_f32_e32 v131, v199, v131
	v_add_f32_e32 v130, v200, v130
	v_add_f32_e32 v131, v201, v131
	v_add_f32_e32 v130, v202, v130
	v_add_f32_e32 v131, v203, v131
	v_add_f32_e32 v130, v204, v130
	v_add_f32_e32 v131, v205, v131
	v_add_f32_e32 v130, v206, v130
	v_add_f32_e32 v131, v207, v131
	v_add_f32_e32 v130, v130, v131
	v_add_f32_e32 v165, v165, v130
	v_add_f32_e32 v132, v208, v209
	v_add_f32_e32 v133, v210, v211
	v_add_f32_e32 v132, v212, v132
	v_add_f32_e32 v133, v213, v133
	v_add_f32_e32 v132, v214, v132
	v_add_f32_e32 v133, v215, v133
	v_add_f32_e32 v132, v216, v132
	v_add_f32_e32 v133, v217, v133
	v_add_f32_e32 v132, v218, v132
	v_add_f32_e32 v133, v219, v133
	v_add_f32_e32 v132, v220, v132
	v_add_f32_e32 v133, v221, v133
	v_add_f32_e32 v132, v222, v132
	v_add_f32_e32 v133, v223, v133
	v_add_f32_e32 v132, v132, v133
	v_add_f32_e32 v163, v163, v132
	v_cvt_pk_bf16_f32 v192, v192, v193
	v_cvt_pk_bf16_f32 v193, v194, v195
	v_cvt_pk_bf16_f32 v194, v196, v197
	v_cvt_pk_bf16_f32 v195, v198, v199
	v_cvt_pk_bf16_f32 v200, v200, v201
	v_cvt_pk_bf16_f32 v201, v202, v203
	v_cvt_pk_bf16_f32 v202, v204, v205
	v_cvt_pk_bf16_f32 v203, v206, v207
	v_cvt_pk_bf16_f32 v208, v208, v209
	v_cvt_pk_bf16_f32 v209, v210, v211
	v_cvt_pk_bf16_f32 v210, v212, v213
	v_cvt_pk_bf16_f32 v211, v214, v215
	v_cvt_pk_bf16_f32 v216, v216, v217
	v_cvt_pk_bf16_f32 v217, v218, v219
	v_cvt_pk_bf16_f32 v218, v220, v221
	v_cvt_pk_bf16_f32 v219, v222, v223
	s_waitcnt lgkmcnt(6)
	v_mfma_f32_16x16x32_bf16 v[2:5], v[192:195], v[166:169], v[2:5]
	v_mfma_f32_16x16x32_bf16 v[34:37], v[208:211], v[166:169], v[34:37]
	ds_read_b64_tr_b16 v[228:229], v147 offset:32768
	ds_read_b64_tr_b16 v[230:231], v147 offset:36864
	v_mfma_f32_16x16x32_bf16 v[6:9], v[192:195], v[170:173], v[6:9]
	v_mfma_f32_16x16x32_bf16 v[38:41], v[208:211], v[170:173], v[38:41]
	ds_read_b64_tr_b16 v[232:233], v148 offset:32768
	ds_read_b64_tr_b16 v[234:235], v148 offset:36864
	s_waitcnt lgkmcnt(6)
	v_mfma_f32_16x16x32_bf16 v[10:13], v[192:195], v[174:177], v[10:13]
	v_mfma_f32_16x16x32_bf16 v[42:45], v[208:211], v[174:177], v[42:45]
	ds_read_b64_tr_b16 v[236:237], v149 offset:32768
	ds_read_b64_tr_b16 v[238:239], v149 offset:36864
	v_mfma_f32_16x16x32_bf16 v[14:17], v[192:195], v[178:181], v[14:17]
	v_mfma_f32_16x16x32_bf16 v[46:49], v[208:211], v[178:181], v[46:49]
	ds_read_b64_tr_b16 v[166:167], v142 offset:40960
	ds_read_b64_tr_b16 v[168:169], v142 offset:45056
	s_waitcnt lgkmcnt(6)
	v_mfma_f32_16x16x32_bf16 v[18:21], v[192:195], v[224:227], v[18:21]
	v_mfma_f32_16x16x32_bf16 v[50:53], v[208:211], v[224:227], v[50:53]
	ds_read_b64_tr_b16 v[170:171], v143 offset:40960
	ds_read_b64_tr_b16 v[172:173], v143 offset:45056
	v_mfma_f32_16x16x32_bf16 v[22:25], v[192:195], v[228:231], v[22:25]
	v_mfma_f32_16x16x32_bf16 v[54:57], v[208:211], v[228:231], v[54:57]
	ds_read_b64_tr_b16 v[174:175], v144 offset:40960
	ds_read_b64_tr_b16 v[176:177], v144 offset:45056
	s_waitcnt lgkmcnt(6)
	v_mfma_f32_16x16x32_bf16 v[26:29], v[192:195], v[232:235], v[26:29]
	v_mfma_f32_16x16x32_bf16 v[58:61], v[208:211], v[232:235], v[58:61]
	ds_read_b64_tr_b16 v[178:179], v145 offset:40960
	ds_read_b64_tr_b16 v[180:181], v145 offset:45056
	v_mfma_f32_16x16x32_bf16 v[30:33], v[192:195], v[236:239], v[30:33]
	v_mfma_f32_16x16x32_bf16 v[62:65], v[208:211], v[236:239], v[62:65]
	ds_read_b64_tr_b16 v[224:225], v146 offset:40960
	ds_read_b64_tr_b16 v[226:227], v146 offset:45056
	s_waitcnt lgkmcnt(6)
	v_mfma_f32_16x16x32_bf16 v[2:5], v[200:203], v[166:169], v[2:5]
	v_mfma_f32_16x16x32_bf16 v[34:37], v[216:219], v[166:169], v[34:37]
	ds_read_b64_tr_b16 v[228:229], v147 offset:40960
	ds_read_b64_tr_b16 v[230:231], v147 offset:45056
	v_mfma_f32_16x16x32_bf16 v[6:9], v[200:203], v[170:173], v[6:9]
	v_mfma_f32_16x16x32_bf16 v[38:41], v[216:219], v[170:173], v[38:41]
	ds_read_b64_tr_b16 v[232:233], v148 offset:40960
	ds_read_b64_tr_b16 v[234:235], v148 offset:45056
	s_waitcnt lgkmcnt(6)
	v_mfma_f32_16x16x32_bf16 v[10:13], v[200:203], v[174:177], v[10:13]
	v_mfma_f32_16x16x32_bf16 v[42:45], v[216:219], v[174:177], v[42:45]
	ds_read_b64_tr_b16 v[236:237], v149 offset:40960
	ds_read_b64_tr_b16 v[238:239], v149 offset:45056
	v_mfma_f32_16x16x32_bf16 v[14:17], v[200:203], v[178:181], v[14:17]
	v_mfma_f32_16x16x32_bf16 v[46:49], v[216:219], v[178:181], v[46:49]
	s_waitcnt lgkmcnt(4)
	v_mfma_f32_16x16x32_bf16 v[18:21], v[200:203], v[224:227], v[18:21]
	v_mfma_f32_16x16x32_bf16 v[50:53], v[216:219], v[224:227], v[50:53]
	v_mfma_f32_16x16x32_bf16 v[22:25], v[200:203], v[228:231], v[22:25]
	v_mfma_f32_16x16x32_bf16 v[54:57], v[216:219], v[228:231], v[54:57]
	s_waitcnt lgkmcnt(0)
	v_mfma_f32_16x16x32_bf16 v[26:29], v[200:203], v[232:235], v[26:29]
	v_mfma_f32_16x16x32_bf16 v[58:61], v[216:219], v[232:235], v[58:61]
	v_mfma_f32_16x16x32_bf16 v[30:33], v[200:203], v[236:239], v[30:33]
	v_mfma_f32_16x16x32_bf16 v[62:65], v[216:219], v[236:239], v[62:65]
	ds_write_b32 v160, v165
	ds_write_b32 v160, v163 offset:256
	s_waitcnt lgkmcnt(0)
	ds_read_b128 v[66:69], v161 offset:0
	ds_read_b128 v[70:73], v161 offset:64
	ds_read_b128 v[74:77], v161 offset:128
	ds_read_b128 v[78:81], v161 offset:192
	ds_read_b128 v[82:85], v161 offset:256
	ds_read_b128 v[86:89], v161 offset:320
	ds_read_b128 v[90:93], v161 offset:384
	ds_read_b128 v[94:97], v161 offset:448
	s_waitcnt lgkmcnt(0)
	v_add_f32_e32 v66, v66, v70
	v_add_f32_e32 v74, v74, v78
	v_add_f32_e32 v66, v66, v74
	v_rcp_f32_e32 v192, v66
	v_add_f32_e32 v67, v67, v71
	v_add_f32_e32 v75, v75, v79
	v_add_f32_e32 v67, v67, v75
	v_rcp_f32_e32 v193, v67
	v_add_f32_e32 v68, v68, v72
	v_add_f32_e32 v76, v76, v80
	v_add_f32_e32 v68, v68, v76
	v_rcp_f32_e32 v194, v68
	v_add_f32_e32 v69, v69, v73
	v_add_f32_e32 v77, v77, v81
	v_add_f32_e32 v69, v69, v77
	v_rcp_f32_e32 v195, v69
	v_add_f32_e32 v82, v82, v86
	v_add_f32_e32 v90, v90, v94
	v_add_f32_e32 v82, v82, v90
	v_rcp_f32_e32 v196, v82
	v_add_f32_e32 v83, v83, v87
	v_add_f32_e32 v91, v91, v95
	v_add_f32_e32 v83, v83, v91
	v_rcp_f32_e32 v197, v83
	v_add_f32_e32 v84, v84, v88
	v_add_f32_e32 v92, v92, v96
	v_add_f32_e32 v84, v84, v92
	v_rcp_f32_e32 v198, v84
	v_add_f32_e32 v85, v85, v89
	v_add_f32_e32 v93, v93, v97
	v_add_f32_e32 v85, v85, v93
	v_rcp_f32_e32 v199, v85
	s_nop 0
	v_mul_f32_e32 v2, v2, v192
	v_mul_f32_e32 v6, v6, v192
	v_cvt_pk_bf16_f32 v200, v2, v6
	global_store_short v156, v200, s[46:47] offset:0
	global_store_short_d16_hi v156, v200, s[46:47] offset:32
	v_mul_f32_e32 v10, v10, v192
	v_mul_f32_e32 v14, v14, v192
	v_cvt_pk_bf16_f32 v201, v10, v14
	global_store_short v156, v201, s[46:47] offset:64
	global_store_short_d16_hi v156, v201, s[46:47] offset:96
	v_mul_f32_e32 v18, v18, v192
	v_mul_f32_e32 v22, v22, v192
	v_cvt_pk_bf16_f32 v202, v18, v22
	global_store_short v156, v202, s[46:47] offset:128
	global_store_short_d16_hi v156, v202, s[46:47] offset:160
	v_mul_f32_e32 v26, v26, v192
	v_mul_f32_e32 v30, v30, v192
	v_cvt_pk_bf16_f32 v203, v26, v30
	global_store_short v156, v203, s[46:47] offset:192
	global_store_short_d16_hi v156, v203, s[46:47] offset:224
	v_mul_f32_e32 v3, v3, v193
	v_mul_f32_e32 v7, v7, v193
	v_cvt_pk_bf16_f32 v204, v3, v7
	global_store_short v156, v204, s[46:47] offset:2048
	global_store_short_d16_hi v156, v204, s[46:47] offset:2080
	v_mul_f32_e32 v11, v11, v193
	v_mul_f32_e32 v15, v15, v193
	v_cvt_pk_bf16_f32 v205, v11, v15
	global_store_short v156, v205, s[46:47] offset:2112
	global_store_short_d16_hi v156, v205, s[46:47] offset:2144
	v_mul_f32_e32 v19, v19, v193
	v_mul_f32_e32 v23, v23, v193
	v_cvt_pk_bf16_f32 v206, v19, v23
	global_store_short v156, v206, s[46:47] offset:2176
	global_store_short_d16_hi v156, v206, s[46:47] offset:2208
	v_mul_f32_e32 v27, v27, v193
	v_mul_f32_e32 v31, v31, v193
	v_cvt_pk_bf16_f32 v207, v27, v31
	global_store_short v156, v207, s[46:47] offset:2240
	global_store_short_d16_hi v156, v207, s[46:47] offset:2272
	v_mul_f32_e32 v4, v4, v194
	v_mul_f32_e32 v8, v8, v194
	v_cvt_pk_bf16_f32 v200, v4, v8
	global_store_short v157, v200, s[46:47] offset:0
	global_store_short_d16_hi v157, v200, s[46:47] offset:32
	v_mul_f32_e32 v12, v12, v194
	v_mul_f32_e32 v16, v16, v194
	v_cvt_pk_bf16_f32 v201, v12, v16
	global_store_short v157, v201, s[46:47] offset:64
	global_store_short_d16_hi v157, v201, s[46:47] offset:96
	v_mul_f32_e32 v20, v20, v194
	v_mul_f32_e32 v24, v24, v194
	v_cvt_pk_bf16_f32 v202, v20, v24
	global_store_short v157, v202, s[46:47] offset:128
	global_store_short_d16_hi v157, v202, s[46:47] offset:160
	v_mul_f32_e32 v28, v28, v194
	v_mul_f32_e32 v32, v32, v194
	v_cvt_pk_bf16_f32 v203, v28, v32
	global_store_short v157, v203, s[46:47] offset:192
	global_store_short_d16_hi v157, v203, s[46:47] offset:224
	v_mul_f32_e32 v5, v5, v195
	v_mul_f32_e32 v9, v9, v195
	v_cvt_pk_bf16_f32 v204, v5, v9
	global_store_short v157, v204, s[46:47] offset:2048
	global_store_short_d16_hi v157, v204, s[46:47] offset:2080
	v_mul_f32_e32 v13, v13, v195
	v_mul_f32_e32 v17, v17, v195
	v_cvt_pk_bf16_f32 v205, v13, v17
	global_store_short v157, v205, s[46:47] offset:2112
	global_store_short_d16_hi v157, v205, s[46:47] offset:2144
	v_mul_f32_e32 v21, v21, v195
	v_mul_f32_e32 v25, v25, v195
	v_cvt_pk_bf16_f32 v206, v21, v25
	global_store_short v157, v206, s[46:47] offset:2176
	global_store_short_d16_hi v157, v206, s[46:47] offset:2208
	v_mul_f32_e32 v29, v29, v195
	v_mul_f32_e32 v33, v33, v195
	v_cvt_pk_bf16_f32 v207, v29, v33
	global_store_short v157, v207, s[46:47] offset:2240
	global_store_short_d16_hi v157, v207, s[46:47] offset:2272
	v_mul_f32_e32 v34, v34, v196
	v_mul_f32_e32 v38, v38, v196
	v_cvt_pk_bf16_f32 v200, v34, v38
	global_store_short v158, v200, s[46:47] offset:0
	global_store_short_d16_hi v158, v200, s[46:47] offset:32
	v_mul_f32_e32 v42, v42, v196
	v_mul_f32_e32 v46, v46, v196
	v_cvt_pk_bf16_f32 v201, v42, v46
	global_store_short v158, v201, s[46:47] offset:64
	global_store_short_d16_hi v158, v201, s[46:47] offset:96
	v_mul_f32_e32 v50, v50, v196
	v_mul_f32_e32 v54, v54, v196
	v_cvt_pk_bf16_f32 v202, v50, v54
	global_store_short v158, v202, s[46:47] offset:128
	global_store_short_d16_hi v158, v202, s[46:47] offset:160
	v_mul_f32_e32 v58, v58, v196
	v_mul_f32_e32 v62, v62, v196
	v_cvt_pk_bf16_f32 v203, v58, v62
	global_store_short v158, v203, s[46:47] offset:192
	global_store_short_d16_hi v158, v203, s[46:47] offset:224
	v_mul_f32_e32 v35, v35, v197
	v_mul_f32_e32 v39, v39, v197
	v_cvt_pk_bf16_f32 v204, v35, v39
	global_store_short v158, v204, s[46:47] offset:2048
	global_store_short_d16_hi v158, v204, s[46:47] offset:2080
	v_mul_f32_e32 v43, v43, v197
	v_mul_f32_e32 v47, v47, v197
	v_cvt_pk_bf16_f32 v205, v43, v47
	global_store_short v158, v205, s[46:47] offset:2112
	global_store_short_d16_hi v158, v205, s[46:47] offset:2144
	v_mul_f32_e32 v51, v51, v197
	v_mul_f32_e32 v55, v55, v197
	v_cvt_pk_bf16_f32 v206, v51, v55
	global_store_short v158, v206, s[46:47] offset:2176
	global_store_short_d16_hi v158, v206, s[46:47] offset:2208
	v_mul_f32_e32 v59, v59, v197
	v_mul_f32_e32 v63, v63, v197
	v_cvt_pk_bf16_f32 v207, v59, v63
	global_store_short v158, v207, s[46:47] offset:2240
	global_store_short_d16_hi v158, v207, s[46:47] offset:2272
	v_mul_f32_e32 v36, v36, v198
	v_mul_f32_e32 v40, v40, v198
	v_cvt_pk_bf16_f32 v200, v36, v40
	global_store_short v159, v200, s[46:47] offset:0
	global_store_short_d16_hi v159, v200, s[46:47] offset:32
	v_mul_f32_e32 v44, v44, v198
	v_mul_f32_e32 v48, v48, v198
	v_cvt_pk_bf16_f32 v201, v44, v48
	global_store_short v159, v201, s[46:47] offset:64
	global_store_short_d16_hi v159, v201, s[46:47] offset:96
	v_mul_f32_e32 v52, v52, v198
	v_mul_f32_e32 v56, v56, v198
	v_cvt_pk_bf16_f32 v202, v52, v56
	global_store_short v159, v202, s[46:47] offset:128
	global_store_short_d16_hi v159, v202, s[46:47] offset:160
	v_mul_f32_e32 v60, v60, v198
	v_mul_f32_e32 v64, v64, v198
	v_cvt_pk_bf16_f32 v203, v60, v64
	global_store_short v159, v203, s[46:47] offset:192
	global_store_short_d16_hi v159, v203, s[46:47] offset:224
	v_mul_f32_e32 v37, v37, v199
	v_mul_f32_e32 v41, v41, v199
	v_cvt_pk_bf16_f32 v204, v37, v41
	global_store_short v159, v204, s[46:47] offset:2048
	global_store_short_d16_hi v159, v204, s[46:47] offset:2080
	v_mul_f32_e32 v45, v45, v199
	v_mul_f32_e32 v49, v49, v199
	v_cvt_pk_bf16_f32 v205, v45, v49
	global_store_short v159, v205, s[46:47] offset:2112
	global_store_short_d16_hi v159, v205, s[46:47] offset:2144
	v_mul_f32_e32 v53, v53, v199
	v_mul_f32_e32 v57, v57, v199
	v_cvt_pk_bf16_f32 v206, v53, v57
	global_store_short v159, v206, s[46:47] offset:2176
	global_store_short_d16_hi v159, v206, s[46:47] offset:2208
	v_mul_f32_e32 v61, v61, v199
	v_mul_f32_e32 v65, v65, v199
	v_cvt_pk_bf16_f32 v207, v61, v65
	global_store_short v159, v207, s[46:47] offset:2240
	global_store_short_d16_hi v159, v207, s[46:47] offset:2272
	s_mov_b32 s46, s18
	s_mov_b32 s47, s19
	v_mov_b32_e32 v2, 0
	v_mov_b32_e32 v3, 0
	v_mov_b32_e32 v4, 0
	v_mov_b32_e32 v5, 0
	v_mov_b32_e32 v6, 0
	v_mov_b32_e32 v7, 0
	v_mov_b32_e32 v8, 0
	v_mov_b32_e32 v9, 0
	v_mov_b32_e32 v10, 0
	v_mov_b32_e32 v11, 0
	v_mov_b32_e32 v12, 0
	v_mov_b32_e32 v13, 0
	v_mov_b32_e32 v14, 0
	v_mov_b32_e32 v15, 0
	v_mov_b32_e32 v16, 0
	v_mov_b32_e32 v17, 0
	v_mov_b32_e32 v18, 0
	v_mov_b32_e32 v19, 0
	v_mov_b32_e32 v20, 0
	v_mov_b32_e32 v21, 0
	v_mov_b32_e32 v22, 0
	v_mov_b32_e32 v23, 0
	v_mov_b32_e32 v24, 0
	v_mov_b32_e32 v25, 0
	v_mov_b32_e32 v26, 0
	v_mov_b32_e32 v27, 0
	v_mov_b32_e32 v28, 0
	v_mov_b32_e32 v29, 0
	v_mov_b32_e32 v30, 0
	v_mov_b32_e32 v31, 0
	v_mov_b32_e32 v32, 0
	v_mov_b32_e32 v33, 0
	v_mov_b32_e32 v34, 0
	v_mov_b32_e32 v35, 0
	v_mov_b32_e32 v36, 0
	v_mov_b32_e32 v37, 0
	v_mov_b32_e32 v38, 0
	v_mov_b32_e32 v39, 0
	v_mov_b32_e32 v40, 0
	v_mov_b32_e32 v41, 0
	v_mov_b32_e32 v42, 0
	v_mov_b32_e32 v43, 0
	v_mov_b32_e32 v44, 0
	v_mov_b32_e32 v45, 0
	v_mov_b32_e32 v46, 0
	v_mov_b32_e32 v47, 0
	v_mov_b32_e32 v48, 0
	v_mov_b32_e32 v49, 0
	v_mov_b32_e32 v50, 0
	v_mov_b32_e32 v51, 0
	v_mov_b32_e32 v52, 0
	v_mov_b32_e32 v53, 0
	v_mov_b32_e32 v54, 0
	v_mov_b32_e32 v55, 0
	v_mov_b32_e32 v56, 0
	v_mov_b32_e32 v57, 0
	v_mov_b32_e32 v58, 0
	v_mov_b32_e32 v59, 0
	v_mov_b32_e32 v60, 0
	v_mov_b32_e32 v61, 0
	v_mov_b32_e32 v62, 0
	v_mov_b32_e32 v63, 0
	v_mov_b32_e32 v64, 0
	v_mov_b32_e32 v65, 0
	v_mov_b32_e32 v165, 0
	v_mov_b32_e32 v163, 0
	s_waitcnt vmcnt(63)
	s_add_i32 s3, s3, s33
	s_cmpk_lt_i32 s3, 0x400
	s_cbranch_scc1 .Lattn_unit
